# phase-2 shift@W tables (cb) rewritten: each item split over the 8 waves of its workgroup by K slice, LDS-broadcast shift values, packed f32 FMA, LDS reduce; compiler loop keeps only the DFT items
# speedup vs baseline: 1.0080x; 1.0080x over previous
; __device__ __forceinline__ void cb_item(const bf16_t* WT, int ldw, int K, int n0, const float* shift, float* out, int ostride, int lane) {
;     const bf16_t* wp = WT + (size_t)(n0 + lane) * ldw;
;     float a[5] = {0.f, 0.f, 0.f, 0.f, 0.f};
; #pragma unroll 4
;     for (int k8 = 0; k8 < K; k8 += 8) {
;         const u32x4 q = *(const u32x4*)(wp + k8);
;         float w[8];
; #pragma unroll
;         for (int e = 0; e < 4; ++e) { w[2 * e] = __uint_as_float(q[e] << 16); w[2 * e + 1] = __uint_as_float(q[e] & 0xffff0000u); }
; #pragma unroll
;         for (int b = 0; b < 5; ++b) { const float* sp = shift + (size_t)b * 9216 + k8;
; #pragma unroll
;             for (int e = 0; e < 8; ++e) a[b] += w[e] * sp[e]; }
;     }
; __device__ __forceinline__ void cb_tables(const Params& p) {
;     const int lane = threadIdx.x & 63, wave = threadIdx.x >> 6, G = gridDim.x;
;     unsigned char* ws = p.ws; const float* MOD = (const float*)(ws + WS_MOD);
;     for (int it = blockIdx.x + G * wave; it < 4 * 88 + 40 + 32; it += 8 * G) {
;         if (it < 352) { const int mi = it / 88, ch = it % 88, layer = mi >> 1, sub = mi & 1;
;             cb_item((const bf16_t*)(ws + WS_W1T + mi * SZ_W1T), D, D, ch * 64, MOD + (size_t)layer * 5 * 9216 + (sub ? 6 : 0) * 1024, (float*)(ws + WS_CB) + (size_t)mi * 5 * NFF1, NFF1, lane); }
;         else if (it < 392) { const int ch = it - 352; cb_item((const bf16_t*)(ws + WS_WABT), D, D, ch * 64, MOD + 3 * 1024, (float*)(ws + WS_CBAB), NAB, lane); }
.LBB0_148:
	s_or_b64 exec, exec, s[22:23]
	s_cmpk_lg_u32 s82, 0x100
	s_cbranch_scc1 .Lcbx_done
	s_mov_b64 s[100:101], exec
	s_mov_b64 exec, -1
	v_readfirstlane_b32 s44, v176
	s_lshr_b32 s44, s44, 6
	v_and_b32_e32 v16, 63, v176
	v_lshlrev_b32_e32 v17, 11, v16
	s_lshl_b32 s45, s44, 14
	v_mov_b32_e32 v26, s45
	v_mul_u32_u24_e32 v18, 0xa0, v16
	v_add_u32_e32 v18, s45, v18
	v_lshlrev_b32_e32 v19, 5, v16
	v_lshlrev_b32_e32 v20, 2, v16
	v_add_u32_e32 v21, 0x10000, v20
	s_cmpk_ge_u32 s84, 0x58
	s_cselect_b32 s41, 1, 0
	s_cmpk_ge_u32 s84, 0xb0
	s_cselect_b32 s42, 1, 0
	s_add_i32 s41, s41, s42
	s_mul_i32 s42, s41, 0x58
	s_sub_i32 s42, s84, s42
	s_mul_i32 s45, s41, 0xb00000
	s_lshl_b32 s0, s42, 17
	s_add_u32 s45, s45, s0
	s_add_u32 s45, s45, 0x200000
	s_add_u32 s34, s80, s45
	s_addc_u32 s35, s81, 0
	s_mov_b32 s45, 0
	s_cmp_eq_u32 s41, 1
	s_cselect_b32 s45, 0x6000, s45
	s_cmp_eq_u32 s41, 2
	s_cselect_b32 s45, 0x2d000, s45
	s_add_u32 s36, s80, s45
	s_addc_u32 s37, s81, 0
	s_mul_i32 s45, s41, 0x1b800
	s_lshl_b32 s0, s42, 8
	s_add_u32 s45, s45, s0
	s_add_u32 s45, s45, 0x100000
	s_add_u32 s38, s80, s45
	s_addc_u32 s39, s81, 0
	s_movk_i32 s40, 0x5800
	s_lshl_b32 s45, s44, 8
	s_add_u32 s0, s34, s45
	s_addc_u32 s1, s35, 0
	global_load_dwordx4 v[28:31], v17, s[0:1]
	global_load_dwordx4 v[32:35], v17, s[0:1] offset:16
	global_load_dwordx4 v[36:39], v17, s[0:1] offset:32
	global_load_dwordx4 v[40:43], v17, s[0:1] offset:48
	global_load_dwordx4 v[44:47], v17, s[0:1] offset:64
	global_load_dwordx4 v[48:51], v17, s[0:1] offset:80
	global_load_dwordx4 v[52:55], v17, s[0:1] offset:96
	global_load_dwordx4 v[56:59], v17, s[0:1] offset:112
	global_load_dwordx4 v[60:63], v17, s[0:1] offset:128
	global_load_dwordx4 v[64:67], v17, s[0:1] offset:144
	global_load_dwordx4 v[68:71], v17, s[0:1] offset:160
	global_load_dwordx4 v[72:75], v17, s[0:1] offset:176
	global_load_dwordx4 v[76:79], v17, s[0:1] offset:192
	global_load_dwordx4 v[80:83], v17, s[0:1] offset:208
	global_load_dwordx4 v[84:87], v17, s[0:1] offset:224
	global_load_dwordx4 v[88:91], v17, s[0:1] offset:240
	s_lshl_b32 s45, s44, 9
	s_add_u32 s0, s36, s45
	s_addc_u32 s1, s37, 0
	global_load_dwordx4 v[92:95], v19, s[0:1]
	global_load_dwordx4 v[96:99], v19, s[0:1] offset:16
	s_add_u32 s0, s0, 0x9000
	s_addc_u32 s1, s1, 0
	global_load_dwordx4 v[100:103], v19, s[0:1]
	global_load_dwordx4 v[104:107], v19, s[0:1] offset:16
	s_add_u32 s0, s0, 0x9000
	s_addc_u32 s1, s1, 0
	global_load_dwordx4 v[108:111], v19, s[0:1]
	global_load_dwordx4 v[112:115], v19, s[0:1] offset:16
	s_add_u32 s0, s0, 0x9000
	s_addc_u32 s1, s1, 0
	global_load_dwordx4 v[116:119], v19, s[0:1]
	global_load_dwordx4 v[120:123], v19, s[0:1] offset:16
	s_add_u32 s0, s0, 0x9000
	s_addc_u32 s1, s1, 0
	global_load_dwordx4 v[124:127], v19, s[0:1]
	global_load_dwordx4 v[128:131], v19, s[0:1] offset:16
	s_waitcnt vmcnt(0)
	ds_write_b128 v18, v[92:95]
	ds_write_b128 v18, v[96:99] offset:16
	ds_write_b128 v18, v[100:103] offset:32
	ds_write_b128 v18, v[104:107] offset:48
	ds_write_b128 v18, v[108:111] offset:64
	ds_write_b128 v18, v[112:115] offset:80
	ds_write_b128 v18, v[116:119] offset:96
	ds_write_b128 v18, v[120:123] offset:112
	ds_write_b128 v18, v[124:127] offset:128
	ds_write_b128 v18, v[128:131] offset:144
	v_mov_b32_e32 v196, 0
	v_mov_b32_e32 v197, 0
	v_mov_b32_e32 v198, 0
	v_mov_b32_e32 v199, 0
	v_mov_b32_e32 v200, 0
	v_mov_b32_e32 v201, 0
	v_mov_b32_e32 v202, 0
	v_mov_b32_e32 v203, 0
	v_mov_b32_e32 v204, 0
	v_mov_b32_e32 v205, 0
	s_waitcnt lgkmcnt(0)
	ds_read_b128 v[92:95], v26
	ds_read_b128 v[96:99], v26 offset:16
	ds_read_b128 v[100:103], v26 offset:32
	ds_read_b128 v[104:107], v26 offset:48
	ds_read_b128 v[108:111], v26 offset:64
	ds_read_b128 v[112:115], v26 offset:80
	ds_read_b128 v[116:119], v26 offset:96
	ds_read_b128 v[120:123], v26 offset:112
	ds_read_b128 v[124:127], v26 offset:128
	ds_read_b128 v[128:131], v26 offset:144
	ds_read_b128 v[132:135], v26 offset:160
	ds_read_b128 v[136:139], v26 offset:176
	ds_read_b128 v[140:143], v26 offset:192
	ds_read_b128 v[144:147], v26 offset:208
	ds_read_b128 v[148:151], v26 offset:224
	ds_read_b128 v[152:155], v26 offset:240
	ds_read_b128 v[156:159], v26 offset:256
	ds_read_b128 v[160:163], v26 offset:272
	ds_read_b128 v[164:167], v26 offset:288
	ds_read_b128 v[168:171], v26 offset:304
	v_lshlrev_b32_e32 v0, 16, v28
	v_and_b32_e32 v1, 0xffff0000, v28
	v_lshlrev_b32_e32 v2, 16, v29
	v_and_b32_e32 v3, 0xffff0000, v29
	v_lshlrev_b32_e32 v4, 16, v30
	v_and_b32_e32 v5, 0xffff0000, v30
	v_lshlrev_b32_e32 v6, 16, v31
	v_and_b32_e32 v7, 0xffff0000, v31
	s_waitcnt lgkmcnt(10)
	v_pk_fma_f32 v[196:197], v[0:1], v[92:93], v[196:197]
	v_pk_fma_f32 v[198:199], v[0:1], v[100:101], v[198:199]
	v_pk_fma_f32 v[200:201], v[0:1], v[108:109], v[200:201]
	v_pk_fma_f32 v[202:203], v[0:1], v[116:117], v[202:203]
	v_pk_fma_f32 v[204:205], v[0:1], v[124:125], v[204:205]
	v_pk_fma_f32 v[196:197], v[2:3], v[94:95], v[196:197]
	v_pk_fma_f32 v[198:199], v[2:3], v[102:103], v[198:199]
	v_pk_fma_f32 v[200:201], v[2:3], v[110:111], v[200:201]
	v_pk_fma_f32 v[202:203], v[2:3], v[118:119], v[202:203]
	v_pk_fma_f32 v[204:205], v[2:3], v[126:127], v[204:205]
	v_pk_fma_f32 v[196:197], v[4:5], v[96:97], v[196:197]
	v_pk_fma_f32 v[198:199], v[4:5], v[104:105], v[198:199]
	v_pk_fma_f32 v[200:201], v[4:5], v[112:113], v[200:201]
	v_pk_fma_f32 v[202:203], v[4:5], v[120:121], v[202:203]
	v_pk_fma_f32 v[204:205], v[4:5], v[128:129], v[204:205]
	v_pk_fma_f32 v[196:197], v[6:7], v[98:99], v[196:197]
	v_pk_fma_f32 v[198:199], v[6:7], v[106:107], v[198:199]
	v_pk_fma_f32 v[200:201], v[6:7], v[114:115], v[200:201]
	v_pk_fma_f32 v[202:203], v[6:7], v[122:123], v[202:203]
	v_pk_fma_f32 v[204:205], v[6:7], v[130:131], v[204:205]
	ds_read_b128 v[92:95], v26 offset:320
	ds_read_b128 v[96:99], v26 offset:336
	ds_read_b128 v[100:103], v26 offset:352
	ds_read_b128 v[104:107], v26 offset:368
	ds_read_b128 v[108:111], v26 offset:384
	ds_read_b128 v[112:115], v26 offset:400
	ds_read_b128 v[116:119], v26 offset:416
	ds_read_b128 v[120:123], v26 offset:432
	ds_read_b128 v[124:127], v26 offset:448
	ds_read_b128 v[128:131], v26 offset:464
	v_lshlrev_b32_e32 v0, 16, v32
	v_and_b32_e32 v1, 0xffff0000, v32
	v_lshlrev_b32_e32 v2, 16, v33
	v_and_b32_e32 v3, 0xffff0000, v33
	v_lshlrev_b32_e32 v4, 16, v34
	v_and_b32_e32 v5, 0xffff0000, v34
	v_lshlrev_b32_e32 v6, 16, v35
	v_and_b32_e32 v7, 0xffff0000, v35
	s_waitcnt lgkmcnt(10)
; __device__ __forceinline__ void cb_item(const bf16_t* WT, int ldw, int K, int n0, const float* shift, float* out, int ostride, int lane) {
;     ...
;     for (int k8 = 0; k8 < K; k8 += 8) {
;         const u32x4 q = *(const u32x4*)(wp + k8);
;         float w[8];
; #pragma unroll
;         for (int e = 0; e < 4; ++e) { w[2 * e] = __uint_as_float(q[e] << 16); w[2 * e + 1] = __uint_as_float(q[e] & 0xffff0000u); }
; #pragma unroll
;         for (int b = 0; b < 5; ++b) { const float* sp = shift + (size_t)b * 9216 + k8;
; #pragma unroll
;             for (int e = 0; e < 8; ++e) a[b] += w[e] * sp[e]; }
	v_pk_fma_f32 v[196:197], v[0:1], v[132:133], v[196:197]
	v_pk_fma_f32 v[198:199], v[0:1], v[140:141], v[198:199]
	v_pk_fma_f32 v[200:201], v[0:1], v[148:149], v[200:201]
	v_pk_fma_f32 v[202:203], v[0:1], v[156:157], v[202:203]
	v_pk_fma_f32 v[204:205], v[0:1], v[164:165], v[204:205]
	v_pk_fma_f32 v[196:197], v[2:3], v[134:135], v[196:197]
	v_pk_fma_f32 v[198:199], v[2:3], v[142:143], v[198:199]
	v_pk_fma_f32 v[200:201], v[2:3], v[150:151], v[200:201]
	v_pk_fma_f32 v[202:203], v[2:3], v[158:159], v[202:203]
	v_pk_fma_f32 v[204:205], v[2:3], v[166:167], v[204:205]
	v_pk_fma_f32 v[196:197], v[4:5], v[136:137], v[196:197]
	v_pk_fma_f32 v[198:199], v[4:5], v[144:145], v[198:199]
	v_pk_fma_f32 v[200:201], v[4:5], v[152:153], v[200:201]
	v_pk_fma_f32 v[202:203], v[4:5], v[160:161], v[202:203]
	v_pk_fma_f32 v[204:205], v[4:5], v[168:169], v[204:205]
	v_pk_fma_f32 v[196:197], v[6:7], v[138:139], v[196:197]
	v_pk_fma_f32 v[198:199], v[6:7], v[146:147], v[198:199]
	v_pk_fma_f32 v[200:201], v[6:7], v[154:155], v[200:201]
	v_pk_fma_f32 v[202:203], v[6:7], v[162:163], v[202:203]
	v_pk_fma_f32 v[204:205], v[6:7], v[170:171], v[204:205]
	ds_read_b128 v[132:135], v26 offset:480
	ds_read_b128 v[136:139], v26 offset:496
	ds_read_b128 v[140:143], v26 offset:512
	ds_read_b128 v[144:147], v26 offset:528
	ds_read_b128 v[148:151], v26 offset:544
	ds_read_b128 v[152:155], v26 offset:560
	ds_read_b128 v[156:159], v26 offset:576
	ds_read_b128 v[160:163], v26 offset:592
	ds_read_b128 v[164:167], v26 offset:608
	ds_read_b128 v[168:171], v26 offset:624
	v_lshlrev_b32_e32 v0, 16, v36
	v_and_b32_e32 v1, 0xffff0000, v36
	v_lshlrev_b32_e32 v2, 16, v37
	v_and_b32_e32 v3, 0xffff0000, v37
	v_lshlrev_b32_e32 v4, 16, v38
	v_and_b32_e32 v5, 0xffff0000, v38
	v_lshlrev_b32_e32 v6, 16, v39
	v_and_b32_e32 v7, 0xffff0000, v39
	s_waitcnt lgkmcnt(10)
	v_pk_fma_f32 v[196:197], v[0:1], v[92:93], v[196:197]
	v_pk_fma_f32 v[198:199], v[0:1], v[100:101], v[198:199]
	v_pk_fma_f32 v[200:201], v[0:1], v[108:109], v[200:201]
	v_pk_fma_f32 v[202:203], v[0:1], v[116:117], v[202:203]
	v_pk_fma_f32 v[204:205], v[0:1], v[124:125], v[204:205]
	v_pk_fma_f32 v[196:197], v[2:3], v[94:95], v[196:197]
	v_pk_fma_f32 v[198:199], v[2:3], v[102:103], v[198:199]
	v_pk_fma_f32 v[200:201], v[2:3], v[110:111], v[200:201]
	v_pk_fma_f32 v[202:203], v[2:3], v[118:119], v[202:203]
	v_pk_fma_f32 v[204:205], v[2:3], v[126:127], v[204:205]
	v_pk_fma_f32 v[196:197], v[4:5], v[96:97], v[196:197]
	v_pk_fma_f32 v[198:199], v[4:5], v[104:105], v[198:199]
	v_pk_fma_f32 v[200:201], v[4:5], v[112:113], v[200:201]
	v_pk_fma_f32 v[202:203], v[4:5], v[120:121], v[202:203]
	v_pk_fma_f32 v[204:205], v[4:5], v[128:129], v[204:205]
	v_pk_fma_f32 v[196:197], v[6:7], v[98:99], v[196:197]
	v_pk_fma_f32 v[198:199], v[6:7], v[106:107], v[198:199]
	v_pk_fma_f32 v[200:201], v[6:7], v[114:115], v[200:201]
	v_pk_fma_f32 v[202:203], v[6:7], v[122:123], v[202:203]
	v_pk_fma_f32 v[204:205], v[6:7], v[130:131], v[204:205]
	ds_read_b128 v[92:95], v26 offset:640
	ds_read_b128 v[96:99], v26 offset:656
	ds_read_b128 v[100:103], v26 offset:672
	ds_read_b128 v[104:107], v26 offset:688
	ds_read_b128 v[108:111], v26 offset:704
	ds_read_b128 v[112:115], v26 offset:720
	ds_read_b128 v[116:119], v26 offset:736
	ds_read_b128 v[120:123], v26 offset:752
	ds_read_b128 v[124:127], v26 offset:768
	ds_read_b128 v[128:131], v26 offset:784
	v_lshlrev_b32_e32 v0, 16, v40
	v_and_b32_e32 v1, 0xffff0000, v40
	v_lshlrev_b32_e32 v2, 16, v41
	v_and_b32_e32 v3, 0xffff0000, v41
	v_lshlrev_b32_e32 v4, 16, v42
	v_and_b32_e32 v5, 0xffff0000, v42
	v_lshlrev_b32_e32 v6, 16, v43
	v_and_b32_e32 v7, 0xffff0000, v43
	s_waitcnt lgkmcnt(10)
	v_pk_fma_f32 v[196:197], v[0:1], v[132:133], v[196:197]
	v_pk_fma_f32 v[198:199], v[0:1], v[140:141], v[198:199]
	v_pk_fma_f32 v[200:201], v[0:1], v[148:149], v[200:201]
	v_pk_fma_f32 v[202:203], v[0:1], v[156:157], v[202:203]
	v_pk_fma_f32 v[204:205], v[0:1], v[164:165], v[204:205]
	v_pk_fma_f32 v[196:197], v[2:3], v[134:135], v[196:197]
	v_pk_fma_f32 v[198:199], v[2:3], v[142:143], v[198:199]
	v_pk_fma_f32 v[200:201], v[2:3], v[150:151], v[200:201]
	v_pk_fma_f32 v[202:203], v[2:3], v[158:159], v[202:203]
	v_pk_fma_f32 v[204:205], v[2:3], v[166:167], v[204:205]
	v_pk_fma_f32 v[196:197], v[4:5], v[136:137], v[196:197]
	v_pk_fma_f32 v[198:199], v[4:5], v[144:145], v[198:199]
	v_pk_fma_f32 v[200:201], v[4:5], v[152:153], v[200:201]
	v_pk_fma_f32 v[202:203], v[4:5], v[160:161], v[202:203]
	v_pk_fma_f32 v[204:205], v[4:5], v[168:169], v[204:205]
	v_pk_fma_f32 v[196:197], v[6:7], v[138:139], v[196:197]
	v_pk_fma_f32 v[198:199], v[6:7], v[146:147], v[198:199]
	v_pk_fma_f32 v[200:201], v[6:7], v[154:155], v[200:201]
	v_pk_fma_f32 v[202:203], v[6:7], v[162:163], v[202:203]
	v_pk_fma_f32 v[204:205], v[6:7], v[170:171], v[204:205]
	ds_read_b128 v[132:135], v26 offset:800
	ds_read_b128 v[136:139], v26 offset:816
	ds_read_b128 v[140:143], v26 offset:832
	ds_read_b128 v[144:147], v26 offset:848
	ds_read_b128 v[148:151], v26 offset:864
	ds_read_b128 v[152:155], v26 offset:880
	ds_read_b128 v[156:159], v26 offset:896
	ds_read_b128 v[160:163], v26 offset:912
	ds_read_b128 v[164:167], v26 offset:928
	ds_read_b128 v[168:171], v26 offset:944
	v_lshlrev_b32_e32 v0, 16, v44
	v_and_b32_e32 v1, 0xffff0000, v44
	v_lshlrev_b32_e32 v2, 16, v45
	v_and_b32_e32 v3, 0xffff0000, v45
	v_lshlrev_b32_e32 v4, 16, v46
	v_and_b32_e32 v5, 0xffff0000, v46
	v_lshlrev_b32_e32 v6, 16, v47
	v_and_b32_e32 v7, 0xffff0000, v47
	s_waitcnt lgkmcnt(10)
; __device__ __forceinline__ void cb_item(const bf16_t* WT, int ldw, int K, int n0, const float* shift, float* out, int ostride, int lane) {
;     ...
;     for (int k8 = 0; k8 < K; k8 += 8) {
;         const u32x4 q = *(const u32x4*)(wp + k8);
;         float w[8];
; #pragma unroll
;         for (int e = 0; e < 4; ++e) { w[2 * e] = __uint_as_float(q[e] << 16); w[2 * e + 1] = __uint_as_float(q[e] & 0xffff0000u); }
; #pragma unroll
;         for (int b = 0; b < 5; ++b) { const float* sp = shift + (size_t)b * 9216 + k8;
; #pragma unroll
;             for (int e = 0; e < 8; ++e) a[b] += w[e] * sp[e]; }
	v_pk_fma_f32 v[196:197], v[0:1], v[92:93], v[196:197]
	v_pk_fma_f32 v[198:199], v[0:1], v[100:101], v[198:199]
	v_pk_fma_f32 v[200:201], v[0:1], v[108:109], v[200:201]
	v_pk_fma_f32 v[202:203], v[0:1], v[116:117], v[202:203]
	v_pk_fma_f32 v[204:205], v[0:1], v[124:125], v[204:205]
	v_pk_fma_f32 v[196:197], v[2:3], v[94:95], v[196:197]
	v_pk_fma_f32 v[198:199], v[2:3], v[102:103], v[198:199]
	v_pk_fma_f32 v[200:201], v[2:3], v[110:111], v[200:201]
	v_pk_fma_f32 v[202:203], v[2:3], v[118:119], v[202:203]
	v_pk_fma_f32 v[204:205], v[2:3], v[126:127], v[204:205]
	v_pk_fma_f32 v[196:197], v[4:5], v[96:97], v[196:197]
	v_pk_fma_f32 v[198:199], v[4:5], v[104:105], v[198:199]
	v_pk_fma_f32 v[200:201], v[4:5], v[112:113], v[200:201]
	v_pk_fma_f32 v[202:203], v[4:5], v[120:121], v[202:203]
	v_pk_fma_f32 v[204:205], v[4:5], v[128:129], v[204:205]
	v_pk_fma_f32 v[196:197], v[6:7], v[98:99], v[196:197]
	v_pk_fma_f32 v[198:199], v[6:7], v[106:107], v[198:199]
	v_pk_fma_f32 v[200:201], v[6:7], v[114:115], v[200:201]
	v_pk_fma_f32 v[202:203], v[6:7], v[122:123], v[202:203]
	v_pk_fma_f32 v[204:205], v[6:7], v[130:131], v[204:205]
	ds_read_b128 v[92:95], v26 offset:960
	ds_read_b128 v[96:99], v26 offset:976
	ds_read_b128 v[100:103], v26 offset:992
	ds_read_b128 v[104:107], v26 offset:1008
	ds_read_b128 v[108:111], v26 offset:1024
	ds_read_b128 v[112:115], v26 offset:1040
	ds_read_b128 v[116:119], v26 offset:1056
	ds_read_b128 v[120:123], v26 offset:1072
	ds_read_b128 v[124:127], v26 offset:1088
	ds_read_b128 v[128:131], v26 offset:1104
	v_lshlrev_b32_e32 v0, 16, v48
	v_and_b32_e32 v1, 0xffff0000, v48
	v_lshlrev_b32_e32 v2, 16, v49
	v_and_b32_e32 v3, 0xffff0000, v49
	v_lshlrev_b32_e32 v4, 16, v50
	v_and_b32_e32 v5, 0xffff0000, v50
	v_lshlrev_b32_e32 v6, 16, v51
	v_and_b32_e32 v7, 0xffff0000, v51
	s_waitcnt lgkmcnt(10)
	v_pk_fma_f32 v[196:197], v[0:1], v[132:133], v[196:197]
	v_pk_fma_f32 v[198:199], v[0:1], v[140:141], v[198:199]
	v_pk_fma_f32 v[200:201], v[0:1], v[148:149], v[200:201]
	v_pk_fma_f32 v[202:203], v[0:1], v[156:157], v[202:203]
	v_pk_fma_f32 v[204:205], v[0:1], v[164:165], v[204:205]
	v_pk_fma_f32 v[196:197], v[2:3], v[134:135], v[196:197]
	v_pk_fma_f32 v[198:199], v[2:3], v[142:143], v[198:199]
	v_pk_fma_f32 v[200:201], v[2:3], v[150:151], v[200:201]
	v_pk_fma_f32 v[202:203], v[2:3], v[158:159], v[202:203]
	v_pk_fma_f32 v[204:205], v[2:3], v[166:167], v[204:205]
	v_pk_fma_f32 v[196:197], v[4:5], v[136:137], v[196:197]
	v_pk_fma_f32 v[198:199], v[4:5], v[144:145], v[198:199]
	v_pk_fma_f32 v[200:201], v[4:5], v[152:153], v[200:201]
	v_pk_fma_f32 v[202:203], v[4:5], v[160:161], v[202:203]
	v_pk_fma_f32 v[204:205], v[4:5], v[168:169], v[204:205]
	v_pk_fma_f32 v[196:197], v[6:7], v[138:139], v[196:197]
	v_pk_fma_f32 v[198:199], v[6:7], v[146:147], v[198:199]
	v_pk_fma_f32 v[200:201], v[6:7], v[154:155], v[200:201]
	v_pk_fma_f32 v[202:203], v[6:7], v[162:163], v[202:203]
	v_pk_fma_f32 v[204:205], v[6:7], v[170:171], v[204:205]
	ds_read_b128 v[132:135], v26 offset:1120
	ds_read_b128 v[136:139], v26 offset:1136
	ds_read_b128 v[140:143], v26 offset:1152
	ds_read_b128 v[144:147], v26 offset:1168
	ds_read_b128 v[148:151], v26 offset:1184
	ds_read_b128 v[152:155], v26 offset:1200
	ds_read_b128 v[156:159], v26 offset:1216
	ds_read_b128 v[160:163], v26 offset:1232
	ds_read_b128 v[164:167], v26 offset:1248
	ds_read_b128 v[168:171], v26 offset:1264
	v_lshlrev_b32_e32 v0, 16, v52
	v_and_b32_e32 v1, 0xffff0000, v52
	v_lshlrev_b32_e32 v2, 16, v53
	v_and_b32_e32 v3, 0xffff0000, v53
	v_lshlrev_b32_e32 v4, 16, v54
	v_and_b32_e32 v5, 0xffff0000, v54
	v_lshlrev_b32_e32 v6, 16, v55
	v_and_b32_e32 v7, 0xffff0000, v55
	s_waitcnt lgkmcnt(10)
	v_pk_fma_f32 v[196:197], v[0:1], v[92:93], v[196:197]
	v_pk_fma_f32 v[198:199], v[0:1], v[100:101], v[198:199]
	v_pk_fma_f32 v[200:201], v[0:1], v[108:109], v[200:201]
	v_pk_fma_f32 v[202:203], v[0:1], v[116:117], v[202:203]
	v_pk_fma_f32 v[204:205], v[0:1], v[124:125], v[204:205]
	v_pk_fma_f32 v[196:197], v[2:3], v[94:95], v[196:197]
	v_pk_fma_f32 v[198:199], v[2:3], v[102:103], v[198:199]
	v_pk_fma_f32 v[200:201], v[2:3], v[110:111], v[200:201]
	v_pk_fma_f32 v[202:203], v[2:3], v[118:119], v[202:203]
	v_pk_fma_f32 v[204:205], v[2:3], v[126:127], v[204:205]
	v_pk_fma_f32 v[196:197], v[4:5], v[96:97], v[196:197]
	v_pk_fma_f32 v[198:199], v[4:5], v[104:105], v[198:199]
	v_pk_fma_f32 v[200:201], v[4:5], v[112:113], v[200:201]
	v_pk_fma_f32 v[202:203], v[4:5], v[120:121], v[202:203]
	v_pk_fma_f32 v[204:205], v[4:5], v[128:129], v[204:205]
	v_pk_fma_f32 v[196:197], v[6:7], v[98:99], v[196:197]
	v_pk_fma_f32 v[198:199], v[6:7], v[106:107], v[198:199]
	v_pk_fma_f32 v[200:201], v[6:7], v[114:115], v[200:201]
	v_pk_fma_f32 v[202:203], v[6:7], v[122:123], v[202:203]
	v_pk_fma_f32 v[204:205], v[6:7], v[130:131], v[204:205]
	ds_read_b128 v[92:95], v26 offset:1280
	ds_read_b128 v[96:99], v26 offset:1296
	ds_read_b128 v[100:103], v26 offset:1312
	ds_read_b128 v[104:107], v26 offset:1328
	ds_read_b128 v[108:111], v26 offset:1344
	ds_read_b128 v[112:115], v26 offset:1360
	ds_read_b128 v[116:119], v26 offset:1376
	ds_read_b128 v[120:123], v26 offset:1392
	ds_read_b128 v[124:127], v26 offset:1408
	ds_read_b128 v[128:131], v26 offset:1424
	v_lshlrev_b32_e32 v0, 16, v56
	v_and_b32_e32 v1, 0xffff0000, v56
	v_lshlrev_b32_e32 v2, 16, v57
	v_and_b32_e32 v3, 0xffff0000, v57
	v_lshlrev_b32_e32 v4, 16, v58
	v_and_b32_e32 v5, 0xffff0000, v58
	v_lshlrev_b32_e32 v6, 16, v59
	v_and_b32_e32 v7, 0xffff0000, v59
	s_waitcnt lgkmcnt(10)
; __device__ __forceinline__ void cb_item(const bf16_t* WT, int ldw, int K, int n0, const float* shift, float* out, int ostride, int lane) {
;     ...
;     for (int k8 = 0; k8 < K; k8 += 8) {
;         const u32x4 q = *(const u32x4*)(wp + k8);
;         float w[8];
; #pragma unroll
;         for (int e = 0; e < 4; ++e) { w[2 * e] = __uint_as_float(q[e] << 16); w[2 * e + 1] = __uint_as_float(q[e] & 0xffff0000u); }
; #pragma unroll
;         for (int b = 0; b < 5; ++b) { const float* sp = shift + (size_t)b * 9216 + k8;
; #pragma unroll
;             for (int e = 0; e < 8; ++e) a[b] += w[e] * sp[e]; }
	v_pk_fma_f32 v[196:197], v[0:1], v[132:133], v[196:197]
	v_pk_fma_f32 v[198:199], v[0:1], v[140:141], v[198:199]
	v_pk_fma_f32 v[200:201], v[0:1], v[148:149], v[200:201]
	v_pk_fma_f32 v[202:203], v[0:1], v[156:157], v[202:203]
	v_pk_fma_f32 v[204:205], v[0:1], v[164:165], v[204:205]
	v_pk_fma_f32 v[196:197], v[2:3], v[134:135], v[196:197]
	v_pk_fma_f32 v[198:199], v[2:3], v[142:143], v[198:199]
	v_pk_fma_f32 v[200:201], v[2:3], v[150:151], v[200:201]
	v_pk_fma_f32 v[202:203], v[2:3], v[158:159], v[202:203]
	v_pk_fma_f32 v[204:205], v[2:3], v[166:167], v[204:205]
	v_pk_fma_f32 v[196:197], v[4:5], v[136:137], v[196:197]
	v_pk_fma_f32 v[198:199], v[4:5], v[144:145], v[198:199]
	v_pk_fma_f32 v[200:201], v[4:5], v[152:153], v[200:201]
	v_pk_fma_f32 v[202:203], v[4:5], v[160:161], v[202:203]
	v_pk_fma_f32 v[204:205], v[4:5], v[168:169], v[204:205]
	v_pk_fma_f32 v[196:197], v[6:7], v[138:139], v[196:197]
	v_pk_fma_f32 v[198:199], v[6:7], v[146:147], v[198:199]
	v_pk_fma_f32 v[200:201], v[6:7], v[154:155], v[200:201]
	v_pk_fma_f32 v[202:203], v[6:7], v[162:163], v[202:203]
	v_pk_fma_f32 v[204:205], v[6:7], v[170:171], v[204:205]
	ds_read_b128 v[132:135], v26 offset:1440
	ds_read_b128 v[136:139], v26 offset:1456
	ds_read_b128 v[140:143], v26 offset:1472
	ds_read_b128 v[144:147], v26 offset:1488
	ds_read_b128 v[148:151], v26 offset:1504
	ds_read_b128 v[152:155], v26 offset:1520
	ds_read_b128 v[156:159], v26 offset:1536
	ds_read_b128 v[160:163], v26 offset:1552
	ds_read_b128 v[164:167], v26 offset:1568
	ds_read_b128 v[168:171], v26 offset:1584
	v_lshlrev_b32_e32 v0, 16, v60
	v_and_b32_e32 v1, 0xffff0000, v60
	v_lshlrev_b32_e32 v2, 16, v61
	v_and_b32_e32 v3, 0xffff0000, v61
	v_lshlrev_b32_e32 v4, 16, v62
	v_and_b32_e32 v5, 0xffff0000, v62
	v_lshlrev_b32_e32 v6, 16, v63
	v_and_b32_e32 v7, 0xffff0000, v63
	s_waitcnt lgkmcnt(10)
	v_pk_fma_f32 v[196:197], v[0:1], v[92:93], v[196:197]
	v_pk_fma_f32 v[198:199], v[0:1], v[100:101], v[198:199]
	v_pk_fma_f32 v[200:201], v[0:1], v[108:109], v[200:201]
	v_pk_fma_f32 v[202:203], v[0:1], v[116:117], v[202:203]
	v_pk_fma_f32 v[204:205], v[0:1], v[124:125], v[204:205]
	v_pk_fma_f32 v[196:197], v[2:3], v[94:95], v[196:197]
	v_pk_fma_f32 v[198:199], v[2:3], v[102:103], v[198:199]
	v_pk_fma_f32 v[200:201], v[2:3], v[110:111], v[200:201]
	v_pk_fma_f32 v[202:203], v[2:3], v[118:119], v[202:203]
	v_pk_fma_f32 v[204:205], v[2:3], v[126:127], v[204:205]
	v_pk_fma_f32 v[196:197], v[4:5], v[96:97], v[196:197]
	v_pk_fma_f32 v[198:199], v[4:5], v[104:105], v[198:199]
	v_pk_fma_f32 v[200:201], v[4:5], v[112:113], v[200:201]
	v_pk_fma_f32 v[202:203], v[4:5], v[120:121], v[202:203]
	v_pk_fma_f32 v[204:205], v[4:5], v[128:129], v[204:205]
	v_pk_fma_f32 v[196:197], v[6:7], v[98:99], v[196:197]
	v_pk_fma_f32 v[198:199], v[6:7], v[106:107], v[198:199]
	v_pk_fma_f32 v[200:201], v[6:7], v[114:115], v[200:201]
	v_pk_fma_f32 v[202:203], v[6:7], v[122:123], v[202:203]
	v_pk_fma_f32 v[204:205], v[6:7], v[130:131], v[204:205]
	ds_read_b128 v[92:95], v26 offset:1600
	ds_read_b128 v[96:99], v26 offset:1616
	ds_read_b128 v[100:103], v26 offset:1632
	ds_read_b128 v[104:107], v26 offset:1648
	ds_read_b128 v[108:111], v26 offset:1664
	ds_read_b128 v[112:115], v26 offset:1680
	ds_read_b128 v[116:119], v26 offset:1696
	ds_read_b128 v[120:123], v26 offset:1712
	ds_read_b128 v[124:127], v26 offset:1728
	ds_read_b128 v[128:131], v26 offset:1744
	v_lshlrev_b32_e32 v0, 16, v64
	v_and_b32_e32 v1, 0xffff0000, v64
	v_lshlrev_b32_e32 v2, 16, v65
	v_and_b32_e32 v3, 0xffff0000, v65
	v_lshlrev_b32_e32 v4, 16, v66
	v_and_b32_e32 v5, 0xffff0000, v66
	v_lshlrev_b32_e32 v6, 16, v67
	v_and_b32_e32 v7, 0xffff0000, v67
	s_waitcnt lgkmcnt(10)
	v_pk_fma_f32 v[196:197], v[0:1], v[132:133], v[196:197]
	v_pk_fma_f32 v[198:199], v[0:1], v[140:141], v[198:199]
	v_pk_fma_f32 v[200:201], v[0:1], v[148:149], v[200:201]
	v_pk_fma_f32 v[202:203], v[0:1], v[156:157], v[202:203]
	v_pk_fma_f32 v[204:205], v[0:1], v[164:165], v[204:205]
	v_pk_fma_f32 v[196:197], v[2:3], v[134:135], v[196:197]
	v_pk_fma_f32 v[198:199], v[2:3], v[142:143], v[198:199]
	v_pk_fma_f32 v[200:201], v[2:3], v[150:151], v[200:201]
	v_pk_fma_f32 v[202:203], v[2:3], v[158:159], v[202:203]
	v_pk_fma_f32 v[204:205], v[2:3], v[166:167], v[204:205]
	v_pk_fma_f32 v[196:197], v[4:5], v[136:137], v[196:197]
	v_pk_fma_f32 v[198:199], v[4:5], v[144:145], v[198:199]
	v_pk_fma_f32 v[200:201], v[4:5], v[152:153], v[200:201]
	v_pk_fma_f32 v[202:203], v[4:5], v[160:161], v[202:203]
	v_pk_fma_f32 v[204:205], v[4:5], v[168:169], v[204:205]
	v_pk_fma_f32 v[196:197], v[6:7], v[138:139], v[196:197]
	v_pk_fma_f32 v[198:199], v[6:7], v[146:147], v[198:199]
	v_pk_fma_f32 v[200:201], v[6:7], v[154:155], v[200:201]
	v_pk_fma_f32 v[202:203], v[6:7], v[162:163], v[202:203]
	v_pk_fma_f32 v[204:205], v[6:7], v[170:171], v[204:205]
	ds_read_b128 v[132:135], v26 offset:1760
	ds_read_b128 v[136:139], v26 offset:1776
	ds_read_b128 v[140:143], v26 offset:1792
	ds_read_b128 v[144:147], v26 offset:1808
	ds_read_b128 v[148:151], v26 offset:1824
	ds_read_b128 v[152:155], v26 offset:1840
	ds_read_b128 v[156:159], v26 offset:1856
	ds_read_b128 v[160:163], v26 offset:1872
	ds_read_b128 v[164:167], v26 offset:1888
	ds_read_b128 v[168:171], v26 offset:1904
	v_lshlrev_b32_e32 v0, 16, v68
	v_and_b32_e32 v1, 0xffff0000, v68
	v_lshlrev_b32_e32 v2, 16, v69
	v_and_b32_e32 v3, 0xffff0000, v69
	v_lshlrev_b32_e32 v4, 16, v70
	v_and_b32_e32 v5, 0xffff0000, v70
	v_lshlrev_b32_e32 v6, 16, v71
	v_and_b32_e32 v7, 0xffff0000, v71
	s_waitcnt lgkmcnt(10)
; __device__ __forceinline__ void cb_item(const bf16_t* WT, int ldw, int K, int n0, const float* shift, float* out, int ostride, int lane) {
;     ...
;     for (int k8 = 0; k8 < K; k8 += 8) {
;         const u32x4 q = *(const u32x4*)(wp + k8);
;         float w[8];
; #pragma unroll
;         for (int e = 0; e < 4; ++e) { w[2 * e] = __uint_as_float(q[e] << 16); w[2 * e + 1] = __uint_as_float(q[e] & 0xffff0000u); }
; #pragma unroll
;         for (int b = 0; b < 5; ++b) { const float* sp = shift + (size_t)b * 9216 + k8;
; #pragma unroll
;             for (int e = 0; e < 8; ++e) a[b] += w[e] * sp[e]; }
	v_pk_fma_f32 v[196:197], v[0:1], v[92:93], v[196:197]
	v_pk_fma_f32 v[198:199], v[0:1], v[100:101], v[198:199]
	v_pk_fma_f32 v[200:201], v[0:1], v[108:109], v[200:201]
	v_pk_fma_f32 v[202:203], v[0:1], v[116:117], v[202:203]
	v_pk_fma_f32 v[204:205], v[0:1], v[124:125], v[204:205]
	v_pk_fma_f32 v[196:197], v[2:3], v[94:95], v[196:197]
	v_pk_fma_f32 v[198:199], v[2:3], v[102:103], v[198:199]
	v_pk_fma_f32 v[200:201], v[2:3], v[110:111], v[200:201]
	v_pk_fma_f32 v[202:203], v[2:3], v[118:119], v[202:203]
	v_pk_fma_f32 v[204:205], v[2:3], v[126:127], v[204:205]
	v_pk_fma_f32 v[196:197], v[4:5], v[96:97], v[196:197]
	v_pk_fma_f32 v[198:199], v[4:5], v[104:105], v[198:199]
	v_pk_fma_f32 v[200:201], v[4:5], v[112:113], v[200:201]
	v_pk_fma_f32 v[202:203], v[4:5], v[120:121], v[202:203]
	v_pk_fma_f32 v[204:205], v[4:5], v[128:129], v[204:205]
	v_pk_fma_f32 v[196:197], v[6:7], v[98:99], v[196:197]
	v_pk_fma_f32 v[198:199], v[6:7], v[106:107], v[198:199]
	v_pk_fma_f32 v[200:201], v[6:7], v[114:115], v[200:201]
	v_pk_fma_f32 v[202:203], v[6:7], v[122:123], v[202:203]
	v_pk_fma_f32 v[204:205], v[6:7], v[130:131], v[204:205]
	ds_read_b128 v[92:95], v26 offset:1920
	ds_read_b128 v[96:99], v26 offset:1936
	ds_read_b128 v[100:103], v26 offset:1952
	ds_read_b128 v[104:107], v26 offset:1968
	ds_read_b128 v[108:111], v26 offset:1984
	ds_read_b128 v[112:115], v26 offset:2000
	ds_read_b128 v[116:119], v26 offset:2016
	ds_read_b128 v[120:123], v26 offset:2032
	ds_read_b128 v[124:127], v26 offset:2048
	ds_read_b128 v[128:131], v26 offset:2064
	v_lshlrev_b32_e32 v0, 16, v72
	v_and_b32_e32 v1, 0xffff0000, v72
	v_lshlrev_b32_e32 v2, 16, v73
	v_and_b32_e32 v3, 0xffff0000, v73
	v_lshlrev_b32_e32 v4, 16, v74
	v_and_b32_e32 v5, 0xffff0000, v74
	v_lshlrev_b32_e32 v6, 16, v75
	v_and_b32_e32 v7, 0xffff0000, v75
	s_waitcnt lgkmcnt(10)
	v_pk_fma_f32 v[196:197], v[0:1], v[132:133], v[196:197]
	v_pk_fma_f32 v[198:199], v[0:1], v[140:141], v[198:199]
	v_pk_fma_f32 v[200:201], v[0:1], v[148:149], v[200:201]
	v_pk_fma_f32 v[202:203], v[0:1], v[156:157], v[202:203]
	v_pk_fma_f32 v[204:205], v[0:1], v[164:165], v[204:205]
	v_pk_fma_f32 v[196:197], v[2:3], v[134:135], v[196:197]
	v_pk_fma_f32 v[198:199], v[2:3], v[142:143], v[198:199]
	v_pk_fma_f32 v[200:201], v[2:3], v[150:151], v[200:201]
	v_pk_fma_f32 v[202:203], v[2:3], v[158:159], v[202:203]
	v_pk_fma_f32 v[204:205], v[2:3], v[166:167], v[204:205]
	v_pk_fma_f32 v[196:197], v[4:5], v[136:137], v[196:197]
	v_pk_fma_f32 v[198:199], v[4:5], v[144:145], v[198:199]
	v_pk_fma_f32 v[200:201], v[4:5], v[152:153], v[200:201]
	v_pk_fma_f32 v[202:203], v[4:5], v[160:161], v[202:203]
	v_pk_fma_f32 v[204:205], v[4:5], v[168:169], v[204:205]
	v_pk_fma_f32 v[196:197], v[6:7], v[138:139], v[196:197]
	v_pk_fma_f32 v[198:199], v[6:7], v[146:147], v[198:199]
	v_pk_fma_f32 v[200:201], v[6:7], v[154:155], v[200:201]
	v_pk_fma_f32 v[202:203], v[6:7], v[162:163], v[202:203]
	v_pk_fma_f32 v[204:205], v[6:7], v[170:171], v[204:205]
	ds_read_b128 v[132:135], v26 offset:2080
	ds_read_b128 v[136:139], v26 offset:2096
	ds_read_b128 v[140:143], v26 offset:2112
	ds_read_b128 v[144:147], v26 offset:2128
	ds_read_b128 v[148:151], v26 offset:2144
	ds_read_b128 v[152:155], v26 offset:2160
	ds_read_b128 v[156:159], v26 offset:2176
	ds_read_b128 v[160:163], v26 offset:2192
	ds_read_b128 v[164:167], v26 offset:2208
	ds_read_b128 v[168:171], v26 offset:2224
	v_lshlrev_b32_e32 v0, 16, v76
	v_and_b32_e32 v1, 0xffff0000, v76
	v_lshlrev_b32_e32 v2, 16, v77
	v_and_b32_e32 v3, 0xffff0000, v77
	v_lshlrev_b32_e32 v4, 16, v78
	v_and_b32_e32 v5, 0xffff0000, v78
	v_lshlrev_b32_e32 v6, 16, v79
	v_and_b32_e32 v7, 0xffff0000, v79
	s_waitcnt lgkmcnt(10)
	v_pk_fma_f32 v[196:197], v[0:1], v[92:93], v[196:197]
	v_pk_fma_f32 v[198:199], v[0:1], v[100:101], v[198:199]
	v_pk_fma_f32 v[200:201], v[0:1], v[108:109], v[200:201]
	v_pk_fma_f32 v[202:203], v[0:1], v[116:117], v[202:203]
	v_pk_fma_f32 v[204:205], v[0:1], v[124:125], v[204:205]
	v_pk_fma_f32 v[196:197], v[2:3], v[94:95], v[196:197]
	v_pk_fma_f32 v[198:199], v[2:3], v[102:103], v[198:199]
	v_pk_fma_f32 v[200:201], v[2:3], v[110:111], v[200:201]
	v_pk_fma_f32 v[202:203], v[2:3], v[118:119], v[202:203]
	v_pk_fma_f32 v[204:205], v[2:3], v[126:127], v[204:205]
	v_pk_fma_f32 v[196:197], v[4:5], v[96:97], v[196:197]
	v_pk_fma_f32 v[198:199], v[4:5], v[104:105], v[198:199]
	v_pk_fma_f32 v[200:201], v[4:5], v[112:113], v[200:201]
	v_pk_fma_f32 v[202:203], v[4:5], v[120:121], v[202:203]
	v_pk_fma_f32 v[204:205], v[4:5], v[128:129], v[204:205]
	v_pk_fma_f32 v[196:197], v[6:7], v[98:99], v[196:197]
	v_pk_fma_f32 v[198:199], v[6:7], v[106:107], v[198:199]
	v_pk_fma_f32 v[200:201], v[6:7], v[114:115], v[200:201]
	v_pk_fma_f32 v[202:203], v[6:7], v[122:123], v[202:203]
	v_pk_fma_f32 v[204:205], v[6:7], v[130:131], v[204:205]
	ds_read_b128 v[92:95], v26 offset:2240
	ds_read_b128 v[96:99], v26 offset:2256
	ds_read_b128 v[100:103], v26 offset:2272
	ds_read_b128 v[104:107], v26 offset:2288
	ds_read_b128 v[108:111], v26 offset:2304
	ds_read_b128 v[112:115], v26 offset:2320
	ds_read_b128 v[116:119], v26 offset:2336
	ds_read_b128 v[120:123], v26 offset:2352
	ds_read_b128 v[124:127], v26 offset:2368
	ds_read_b128 v[128:131], v26 offset:2384
	v_lshlrev_b32_e32 v0, 16, v80
	v_and_b32_e32 v1, 0xffff0000, v80
	v_lshlrev_b32_e32 v2, 16, v81
	v_and_b32_e32 v3, 0xffff0000, v81
	v_lshlrev_b32_e32 v4, 16, v82
	v_and_b32_e32 v5, 0xffff0000, v82
	v_lshlrev_b32_e32 v6, 16, v83
	v_and_b32_e32 v7, 0xffff0000, v83
	s_waitcnt lgkmcnt(10)
; __device__ __forceinline__ void cb_item(const bf16_t* WT, int ldw, int K, int n0, const float* shift, float* out, int ostride, int lane) {
;     ...
;     for (int k8 = 0; k8 < K; k8 += 8) {
;         const u32x4 q = *(const u32x4*)(wp + k8);
;         float w[8];
; #pragma unroll
;         for (int e = 0; e < 4; ++e) { w[2 * e] = __uint_as_float(q[e] << 16); w[2 * e + 1] = __uint_as_float(q[e] & 0xffff0000u); }
; #pragma unroll
;         for (int b = 0; b < 5; ++b) { const float* sp = shift + (size_t)b * 9216 + k8;
; #pragma unroll
;             for (int e = 0; e < 8; ++e) a[b] += w[e] * sp[e]; }
;     }
; #pragma unroll
;     for (int b = 0; b < 5; ++b) out[(size_t)b * ostride + n0 + lane] = a[b];
	v_pk_fma_f32 v[196:197], v[0:1], v[132:133], v[196:197]
	v_pk_fma_f32 v[198:199], v[0:1], v[140:141], v[198:199]
	v_pk_fma_f32 v[200:201], v[0:1], v[148:149], v[200:201]
	v_pk_fma_f32 v[202:203], v[0:1], v[156:157], v[202:203]
	v_pk_fma_f32 v[204:205], v[0:1], v[164:165], v[204:205]
	v_pk_fma_f32 v[196:197], v[2:3], v[134:135], v[196:197]
	v_pk_fma_f32 v[198:199], v[2:3], v[142:143], v[198:199]
	v_pk_fma_f32 v[200:201], v[2:3], v[150:151], v[200:201]
	v_pk_fma_f32 v[202:203], v[2:3], v[158:159], v[202:203]
	v_pk_fma_f32 v[204:205], v[2:3], v[166:167], v[204:205]
	v_pk_fma_f32 v[196:197], v[4:5], v[136:137], v[196:197]
	v_pk_fma_f32 v[198:199], v[4:5], v[144:145], v[198:199]
	v_pk_fma_f32 v[200:201], v[4:5], v[152:153], v[200:201]
	v_pk_fma_f32 v[202:203], v[4:5], v[160:161], v[202:203]
	v_pk_fma_f32 v[204:205], v[4:5], v[168:169], v[204:205]
	v_pk_fma_f32 v[196:197], v[6:7], v[138:139], v[196:197]
	v_pk_fma_f32 v[198:199], v[6:7], v[146:147], v[198:199]
	v_pk_fma_f32 v[200:201], v[6:7], v[154:155], v[200:201]
	v_pk_fma_f32 v[202:203], v[6:7], v[162:163], v[202:203]
	v_pk_fma_f32 v[204:205], v[6:7], v[170:171], v[204:205]
	ds_read_b128 v[132:135], v26 offset:2400
	ds_read_b128 v[136:139], v26 offset:2416
	ds_read_b128 v[140:143], v26 offset:2432
	ds_read_b128 v[144:147], v26 offset:2448
	ds_read_b128 v[148:151], v26 offset:2464
	ds_read_b128 v[152:155], v26 offset:2480
	ds_read_b128 v[156:159], v26 offset:2496
	ds_read_b128 v[160:163], v26 offset:2512
	ds_read_b128 v[164:167], v26 offset:2528
	ds_read_b128 v[168:171], v26 offset:2544
	v_lshlrev_b32_e32 v0, 16, v84
	v_and_b32_e32 v1, 0xffff0000, v84
	v_lshlrev_b32_e32 v2, 16, v85
	v_and_b32_e32 v3, 0xffff0000, v85
	v_lshlrev_b32_e32 v4, 16, v86
	v_and_b32_e32 v5, 0xffff0000, v86
	v_lshlrev_b32_e32 v6, 16, v87
	v_and_b32_e32 v7, 0xffff0000, v87
	s_waitcnt lgkmcnt(10)
	v_pk_fma_f32 v[196:197], v[0:1], v[92:93], v[196:197]
	v_pk_fma_f32 v[198:199], v[0:1], v[100:101], v[198:199]
	v_pk_fma_f32 v[200:201], v[0:1], v[108:109], v[200:201]
	v_pk_fma_f32 v[202:203], v[0:1], v[116:117], v[202:203]
	v_pk_fma_f32 v[204:205], v[0:1], v[124:125], v[204:205]
	v_pk_fma_f32 v[196:197], v[2:3], v[94:95], v[196:197]
	v_pk_fma_f32 v[198:199], v[2:3], v[102:103], v[198:199]
	v_pk_fma_f32 v[200:201], v[2:3], v[110:111], v[200:201]
	v_pk_fma_f32 v[202:203], v[2:3], v[118:119], v[202:203]
	v_pk_fma_f32 v[204:205], v[2:3], v[126:127], v[204:205]
	v_pk_fma_f32 v[196:197], v[4:5], v[96:97], v[196:197]
	v_pk_fma_f32 v[198:199], v[4:5], v[104:105], v[198:199]
	v_pk_fma_f32 v[200:201], v[4:5], v[112:113], v[200:201]
	v_pk_fma_f32 v[202:203], v[4:5], v[120:121], v[202:203]
	v_pk_fma_f32 v[204:205], v[4:5], v[128:129], v[204:205]
	v_pk_fma_f32 v[196:197], v[6:7], v[98:99], v[196:197]
	v_pk_fma_f32 v[198:199], v[6:7], v[106:107], v[198:199]
	v_pk_fma_f32 v[200:201], v[6:7], v[114:115], v[200:201]
	v_pk_fma_f32 v[202:203], v[6:7], v[122:123], v[202:203]
	v_pk_fma_f32 v[204:205], v[6:7], v[130:131], v[204:205]
	v_lshlrev_b32_e32 v0, 16, v88
	v_and_b32_e32 v1, 0xffff0000, v88
	v_lshlrev_b32_e32 v2, 16, v89
	v_and_b32_e32 v3, 0xffff0000, v89
	v_lshlrev_b32_e32 v4, 16, v90
	v_and_b32_e32 v5, 0xffff0000, v90
	v_lshlrev_b32_e32 v6, 16, v91
	v_and_b32_e32 v7, 0xffff0000, v91
	s_waitcnt lgkmcnt(0)
	v_pk_fma_f32 v[196:197], v[0:1], v[132:133], v[196:197]
	v_pk_fma_f32 v[198:199], v[0:1], v[140:141], v[198:199]
	v_pk_fma_f32 v[200:201], v[0:1], v[148:149], v[200:201]
	v_pk_fma_f32 v[202:203], v[0:1], v[156:157], v[202:203]
	v_pk_fma_f32 v[204:205], v[0:1], v[164:165], v[204:205]
	v_pk_fma_f32 v[196:197], v[2:3], v[134:135], v[196:197]
	v_pk_fma_f32 v[198:199], v[2:3], v[142:143], v[198:199]
	v_pk_fma_f32 v[200:201], v[2:3], v[150:151], v[200:201]
	v_pk_fma_f32 v[202:203], v[2:3], v[158:159], v[202:203]
	v_pk_fma_f32 v[204:205], v[2:3], v[166:167], v[204:205]
	v_pk_fma_f32 v[196:197], v[4:5], v[136:137], v[196:197]
	v_pk_fma_f32 v[198:199], v[4:5], v[144:145], v[198:199]
	v_pk_fma_f32 v[200:201], v[4:5], v[152:153], v[200:201]
	v_pk_fma_f32 v[202:203], v[4:5], v[160:161], v[202:203]
	v_pk_fma_f32 v[204:205], v[4:5], v[168:169], v[204:205]
	v_pk_fma_f32 v[196:197], v[6:7], v[138:139], v[196:197]
	v_pk_fma_f32 v[198:199], v[6:7], v[146:147], v[198:199]
	v_pk_fma_f32 v[200:201], v[6:7], v[154:155], v[200:201]
	v_pk_fma_f32 v[202:203], v[6:7], v[162:163], v[202:203]
	v_pk_fma_f32 v[204:205], v[6:7], v[170:171], v[204:205]
	v_add_f32_e32 v206, v196, v197
	v_add_f32_e32 v207, v198, v199
	v_add_f32_e32 v208, v200, v201
	v_add_f32_e32 v209, v202, v203
	v_add_f32_e32 v210, v204, v205
	v_add_u32_e32 v27, v26, v20
	ds_write_b32 v27, v206 offset:10240
	ds_write_b32 v27, v207 offset:10496
	ds_write_b32 v27, v208 offset:10752
	ds_write_b32 v27, v209 offset:11008
	ds_write_b32 v27, v210 offset:11264
	s_waitcnt lgkmcnt(0)
	s_barrier
	s_cmp_lg_u32 s44, 0
	s_cbranch_scc1 .Lcbx_nw0_i0
; __device__ __forceinline__ void cb_item(const bf16_t* WT, int ldw, int K, int n0, const float* shift, float* out, int ostride, int lane) {
;     ...
; #pragma unroll
;     for (int b = 0; b < 5; ++b) out[(size_t)b * ostride + n0 + lane] = a[b];
; __device__ __forceinline__ void cb_tables(const Params& p) {
;     ...
;     for (int it = blockIdx.x + G * wave; it < 4 * 88 + 40 + 32; it += 8 * G) {
;         if (it < 352) { const int mi = it / 88, ch = it % 88, layer = mi >> 1, sub = mi & 1;
;             cb_item((const bf16_t*)(ws + WS_W1T + mi * SZ_W1T), D, D, ch * 64, MOD + (size_t)layer * 5 * 9216 + (sub ? 6 : 0) * 1024, (float*)(ws + WS_CB) + (size_t)mi * 5 * NFF1, NFF1, lane); }
;         else if (it < 392) { const int ch = it - 352; cb_item((const bf16_t*)(ws + WS_WABT), D, D, ch * 64, MOD + 3 * 1024, (float*)(ws + WS_CBAB), NAB, lane); }
	ds_read_b32 v28, v20 offset:10240
	ds_read_b32 v29, v20 offset:26624
	ds_read_b32 v30, v20 offset:43008
	ds_read_b32 v31, v20 offset:59392
	ds_read_b32 v32, v21 offset:10240
	ds_read_b32 v33, v21 offset:26624
	ds_read_b32 v34, v21 offset:43008
	ds_read_b32 v35, v21 offset:59392
	ds_read_b32 v36, v20 offset:10496
	ds_read_b32 v37, v20 offset:26880
	ds_read_b32 v38, v20 offset:43264
	ds_read_b32 v39, v20 offset:59648
	ds_read_b32 v40, v21 offset:10496
	ds_read_b32 v41, v21 offset:26880
	ds_read_b32 v42, v21 offset:43264
	ds_read_b32 v43, v21 offset:59648
	ds_read_b32 v44, v20 offset:10752
	ds_read_b32 v45, v20 offset:27136
	ds_read_b32 v46, v20 offset:43520
	ds_read_b32 v47, v20 offset:59904
	ds_read_b32 v48, v21 offset:10752
	ds_read_b32 v49, v21 offset:27136
	ds_read_b32 v50, v21 offset:43520
	ds_read_b32 v51, v21 offset:59904
	ds_read_b32 v52, v20 offset:11008
	ds_read_b32 v53, v20 offset:27392
	ds_read_b32 v54, v20 offset:43776
	ds_read_b32 v55, v20 offset:60160
	ds_read_b32 v56, v21 offset:11008
	ds_read_b32 v57, v21 offset:27392
	ds_read_b32 v58, v21 offset:43776
	ds_read_b32 v59, v21 offset:60160
	ds_read_b32 v60, v20 offset:11264
	ds_read_b32 v61, v20 offset:27648
	ds_read_b32 v62, v20 offset:44032
	ds_read_b32 v63, v20 offset:60416
	ds_read_b32 v64, v21 offset:11264
	ds_read_b32 v65, v21 offset:27648
	ds_read_b32 v66, v21 offset:44032
	ds_read_b32 v67, v21 offset:60416
	s_mov_b64 s[0:1], s[38:39]
	s_waitcnt lgkmcnt(15)
	v_add_f32_e32 v206, v28, v29
	v_add_f32_e32 v206, v206, v30
	v_add_f32_e32 v206, v206, v31
	v_add_f32_e32 v206, v206, v32
	v_add_f32_e32 v206, v206, v33
	v_add_f32_e32 v206, v206, v34
	v_add_f32_e32 v206, v206, v35
	global_store_dword v20, v206, s[0:1]
	s_add_u32 s0, s0, s40
	s_addc_u32 s1, s1, 0
	s_waitcnt lgkmcnt(15)
	v_add_f32_e32 v207, v36, v37
	v_add_f32_e32 v207, v207, v38
	v_add_f32_e32 v207, v207, v39
	v_add_f32_e32 v207, v207, v40
	v_add_f32_e32 v207, v207, v41
	v_add_f32_e32 v207, v207, v42
	v_add_f32_e32 v207, v207, v43
	global_store_dword v20, v207, s[0:1]
	s_add_u32 s0, s0, s40
	s_addc_u32 s1, s1, 0
	s_waitcnt lgkmcnt(15)
	v_add_f32_e32 v208, v44, v45
	v_add_f32_e32 v208, v208, v46
	v_add_f32_e32 v208, v208, v47
	v_add_f32_e32 v208, v208, v48
	v_add_f32_e32 v208, v208, v49
	v_add_f32_e32 v208, v208, v50
	v_add_f32_e32 v208, v208, v51
	global_store_dword v20, v208, s[0:1]
	s_add_u32 s0, s0, s40
	s_addc_u32 s1, s1, 0
	s_waitcnt lgkmcnt(8)
	v_add_f32_e32 v209, v52, v53
	v_add_f32_e32 v209, v209, v54
	v_add_f32_e32 v209, v209, v55
	v_add_f32_e32 v209, v209, v56
	v_add_f32_e32 v209, v209, v57
	v_add_f32_e32 v209, v209, v58
	v_add_f32_e32 v209, v209, v59
	global_store_dword v20, v209, s[0:1]
	s_add_u32 s0, s0, s40
	s_addc_u32 s1, s1, 0
	s_waitcnt lgkmcnt(0)
	v_add_f32_e32 v210, v60, v61
	v_add_f32_e32 v210, v210, v62
	v_add_f32_e32 v210, v210, v63
	v_add_f32_e32 v210, v210, v64
	v_add_f32_e32 v210, v210, v65
	v_add_f32_e32 v210, v210, v66
	v_add_f32_e32 v210, v210, v67
	global_store_dword v20, v210, s[0:1]
.Lcbx_nw0_i0:
	s_barrier
	s_cmpk_lt_u32 s84, 8
	s_cbranch_scc0 .Lcbx_i1_ab
	s_mov_b32 s41, 2
	s_add_i32 s42, s84, 0x50
	s_mul_i32 s45, s41, 0xb00000
	s_lshl_b32 s0, s42, 17
	s_add_u32 s45, s45, s0
	s_add_u32 s45, s45, 0x200000
	s_add_u32 s34, s80, s45
	s_addc_u32 s35, s81, 0
	s_mov_b32 s45, 0
	s_cmp_eq_u32 s41, 1
	s_cselect_b32 s45, 0x6000, s45
	s_cmp_eq_u32 s41, 2
	s_cselect_b32 s45, 0x2d000, s45
	s_add_u32 s36, s80, s45
	s_addc_u32 s37, s81, 0
	s_mul_i32 s45, s41, 0x1b800
	s_lshl_b32 s0, s42, 8
	s_add_u32 s45, s45, s0
	s_add_u32 s45, s45, 0x100000
	s_add_u32 s38, s80, s45
	s_addc_u32 s39, s81, 0
	s_movk_i32 s40, 0x5800
	s_branch .Lcbx_i1_go
.Lcbx_i1_ab:
	s_cmpk_lt_u32 s84, 0x60
	s_cbranch_scc1 .Lcbx_fin
	s_cmpk_ge_u32 s84, 0x88
	s_cbranch_scc1 .Lcbx_fin
	s_sub_i32 s42, s84, 0x60
	s_lshl_b32 s45, s42, 17
	s_add_u32 s45, s45, 0x4400000
	s_add_u32 s34, s80, s45
	s_addc_u32 s35, s81, 0
	s_add_u32 s36, s80, 0x3000
	s_addc_u32 s37, s81, 0
	s_lshl_b32 s45, s42, 8
	s_add_u32 s45, s45, 0x16e000
	s_add_u32 s38, s80, s45
	s_addc_u32 s39, s81, 0
	s_movk_i32 s40, 0x2800
.Lcbx_i1_go:
	s_lshl_b32 s45, s44, 8
	s_add_u32 s0, s34, s45
	s_addc_u32 s1, s35, 0
	global_load_dwordx4 v[28:31], v17, s[0:1]
	global_load_dwordx4 v[32:35], v17, s[0:1] offset:16
	global_load_dwordx4 v[36:39], v17, s[0:1] offset:32
	global_load_dwordx4 v[40:43], v17, s[0:1] offset:48
	global_load_dwordx4 v[44:47], v17, s[0:1] offset:64
	global_load_dwordx4 v[48:51], v17, s[0:1] offset:80
	global_load_dwordx4 v[52:55], v17, s[0:1] offset:96
	global_load_dwordx4 v[56:59], v17, s[0:1] offset:112
	global_load_dwordx4 v[60:63], v17, s[0:1] offset:128
	global_load_dwordx4 v[64:67], v17, s[0:1] offset:144
	global_load_dwordx4 v[68:71], v17, s[0:1] offset:160
	global_load_dwordx4 v[72:75], v17, s[0:1] offset:176
	global_load_dwordx4 v[76:79], v17, s[0:1] offset:192
	global_load_dwordx4 v[80:83], v17, s[0:1] offset:208
	global_load_dwordx4 v[84:87], v17, s[0:1] offset:224
	global_load_dwordx4 v[88:91], v17, s[0:1] offset:240
	s_lshl_b32 s45, s44, 9
	s_add_u32 s0, s36, s45
	s_addc_u32 s1, s37, 0
	global_load_dwordx4 v[92:95], v19, s[0:1]
	global_load_dwordx4 v[96:99], v19, s[0:1] offset:16
	s_add_u32 s0, s0, 0x9000
	s_addc_u32 s1, s1, 0
	global_load_dwordx4 v[100:103], v19, s[0:1]
	global_load_dwordx4 v[104:107], v19, s[0:1] offset:16
	s_add_u32 s0, s0, 0x9000
	s_addc_u32 s1, s1, 0
	global_load_dwordx4 v[108:111], v19, s[0:1]
	global_load_dwordx4 v[112:115], v19, s[0:1] offset:16
	s_add_u32 s0, s0, 0x9000
	s_addc_u32 s1, s1, 0
	global_load_dwordx4 v[116:119], v19, s[0:1]
	global_load_dwordx4 v[120:123], v19, s[0:1] offset:16
	s_add_u32 s0, s0, 0x9000
	s_addc_u32 s1, s1, 0
	global_load_dwordx4 v[124:127], v19, s[0:1]
	global_load_dwordx4 v[128:131], v19, s[0:1] offset:16
	s_waitcnt vmcnt(0)
; __device__ __forceinline__ void cb_item(const bf16_t* WT, int ldw, int K, int n0, const float* shift, float* out, int ostride, int lane) {
;     ...
;     for (int k8 = 0; k8 < K; k8 += 8) {
;         const u32x4 q = *(const u32x4*)(wp + k8);
;         float w[8];
; #pragma unroll
;         for (int e = 0; e < 4; ++e) { w[2 * e] = __uint_as_float(q[e] << 16); w[2 * e + 1] = __uint_as_float(q[e] & 0xffff0000u); }
; #pragma unroll
;         for (int b = 0; b < 5; ++b) { const float* sp = shift + (size_t)b * 9216 + k8;
; #pragma unroll
;             for (int e = 0; e < 8; ++e) a[b] += w[e] * sp[e]; }
	ds_write_b128 v18, v[92:95]
	ds_write_b128 v18, v[96:99] offset:16
	ds_write_b128 v18, v[100:103] offset:32
	ds_write_b128 v18, v[104:107] offset:48
	ds_write_b128 v18, v[108:111] offset:64
	ds_write_b128 v18, v[112:115] offset:80
	ds_write_b128 v18, v[116:119] offset:96
	ds_write_b128 v18, v[120:123] offset:112
	ds_write_b128 v18, v[124:127] offset:128
	ds_write_b128 v18, v[128:131] offset:144
	v_mov_b32_e32 v196, 0
	v_mov_b32_e32 v197, 0
	v_mov_b32_e32 v198, 0
	v_mov_b32_e32 v199, 0
	v_mov_b32_e32 v200, 0
	v_mov_b32_e32 v201, 0
	v_mov_b32_e32 v202, 0
	v_mov_b32_e32 v203, 0
	v_mov_b32_e32 v204, 0
	v_mov_b32_e32 v205, 0
	s_waitcnt lgkmcnt(0)
	ds_read_b128 v[92:95], v26
	ds_read_b128 v[96:99], v26 offset:16
	ds_read_b128 v[100:103], v26 offset:32
	ds_read_b128 v[104:107], v26 offset:48
	ds_read_b128 v[108:111], v26 offset:64
	ds_read_b128 v[112:115], v26 offset:80
	ds_read_b128 v[116:119], v26 offset:96
	ds_read_b128 v[120:123], v26 offset:112
	ds_read_b128 v[124:127], v26 offset:128
	ds_read_b128 v[128:131], v26 offset:144
	ds_read_b128 v[132:135], v26 offset:160
	ds_read_b128 v[136:139], v26 offset:176
	ds_read_b128 v[140:143], v26 offset:192
	ds_read_b128 v[144:147], v26 offset:208
	ds_read_b128 v[148:151], v26 offset:224
	ds_read_b128 v[152:155], v26 offset:240
	ds_read_b128 v[156:159], v26 offset:256
	ds_read_b128 v[160:163], v26 offset:272
	ds_read_b128 v[164:167], v26 offset:288
	ds_read_b128 v[168:171], v26 offset:304
	v_lshlrev_b32_e32 v0, 16, v28
	v_and_b32_e32 v1, 0xffff0000, v28
	v_lshlrev_b32_e32 v2, 16, v29
	v_and_b32_e32 v3, 0xffff0000, v29
	v_lshlrev_b32_e32 v4, 16, v30
	v_and_b32_e32 v5, 0xffff0000, v30
	v_lshlrev_b32_e32 v6, 16, v31
	v_and_b32_e32 v7, 0xffff0000, v31
	s_waitcnt lgkmcnt(10)
	v_pk_fma_f32 v[196:197], v[0:1], v[92:93], v[196:197]
	v_pk_fma_f32 v[198:199], v[0:1], v[100:101], v[198:199]
	v_pk_fma_f32 v[200:201], v[0:1], v[108:109], v[200:201]
	v_pk_fma_f32 v[202:203], v[0:1], v[116:117], v[202:203]
	v_pk_fma_f32 v[204:205], v[0:1], v[124:125], v[204:205]
	v_pk_fma_f32 v[196:197], v[2:3], v[94:95], v[196:197]
	v_pk_fma_f32 v[198:199], v[2:3], v[102:103], v[198:199]
	v_pk_fma_f32 v[200:201], v[2:3], v[110:111], v[200:201]
	v_pk_fma_f32 v[202:203], v[2:3], v[118:119], v[202:203]
	v_pk_fma_f32 v[204:205], v[2:3], v[126:127], v[204:205]
	v_pk_fma_f32 v[196:197], v[4:5], v[96:97], v[196:197]
	v_pk_fma_f32 v[198:199], v[4:5], v[104:105], v[198:199]
	v_pk_fma_f32 v[200:201], v[4:5], v[112:113], v[200:201]
	v_pk_fma_f32 v[202:203], v[4:5], v[120:121], v[202:203]
	v_pk_fma_f32 v[204:205], v[4:5], v[128:129], v[204:205]
	v_pk_fma_f32 v[196:197], v[6:7], v[98:99], v[196:197]
	v_pk_fma_f32 v[198:199], v[6:7], v[106:107], v[198:199]
	v_pk_fma_f32 v[200:201], v[6:7], v[114:115], v[200:201]
	v_pk_fma_f32 v[202:203], v[6:7], v[122:123], v[202:203]
	v_pk_fma_f32 v[204:205], v[6:7], v[130:131], v[204:205]
	ds_read_b128 v[92:95], v26 offset:320
	ds_read_b128 v[96:99], v26 offset:336
	ds_read_b128 v[100:103], v26 offset:352
	ds_read_b128 v[104:107], v26 offset:368
	ds_read_b128 v[108:111], v26 offset:384
	ds_read_b128 v[112:115], v26 offset:400
	ds_read_b128 v[116:119], v26 offset:416
	ds_read_b128 v[120:123], v26 offset:432
	ds_read_b128 v[124:127], v26 offset:448
	ds_read_b128 v[128:131], v26 offset:464
	v_lshlrev_b32_e32 v0, 16, v32
	v_and_b32_e32 v1, 0xffff0000, v32
	v_lshlrev_b32_e32 v2, 16, v33
	v_and_b32_e32 v3, 0xffff0000, v33
	v_lshlrev_b32_e32 v4, 16, v34
	v_and_b32_e32 v5, 0xffff0000, v34
	v_lshlrev_b32_e32 v6, 16, v35
	v_and_b32_e32 v7, 0xffff0000, v35
	s_waitcnt lgkmcnt(10)
	v_pk_fma_f32 v[196:197], v[0:1], v[132:133], v[196:197]
	v_pk_fma_f32 v[198:199], v[0:1], v[140:141], v[198:199]
	v_pk_fma_f32 v[200:201], v[0:1], v[148:149], v[200:201]
	v_pk_fma_f32 v[202:203], v[0:1], v[156:157], v[202:203]
	v_pk_fma_f32 v[204:205], v[0:1], v[164:165], v[204:205]
	v_pk_fma_f32 v[196:197], v[2:3], v[134:135], v[196:197]
	v_pk_fma_f32 v[198:199], v[2:3], v[142:143], v[198:199]
	v_pk_fma_f32 v[200:201], v[2:3], v[150:151], v[200:201]
	v_pk_fma_f32 v[202:203], v[2:3], v[158:159], v[202:203]
	v_pk_fma_f32 v[204:205], v[2:3], v[166:167], v[204:205]
	v_pk_fma_f32 v[196:197], v[4:5], v[136:137], v[196:197]
	v_pk_fma_f32 v[198:199], v[4:5], v[144:145], v[198:199]
	v_pk_fma_f32 v[200:201], v[4:5], v[152:153], v[200:201]
	v_pk_fma_f32 v[202:203], v[4:5], v[160:161], v[202:203]
	v_pk_fma_f32 v[204:205], v[4:5], v[168:169], v[204:205]
	v_pk_fma_f32 v[196:197], v[6:7], v[138:139], v[196:197]
	v_pk_fma_f32 v[198:199], v[6:7], v[146:147], v[198:199]
	v_pk_fma_f32 v[200:201], v[6:7], v[154:155], v[200:201]
	v_pk_fma_f32 v[202:203], v[6:7], v[162:163], v[202:203]
	v_pk_fma_f32 v[204:205], v[6:7], v[170:171], v[204:205]
	ds_read_b128 v[132:135], v26 offset:480
	ds_read_b128 v[136:139], v26 offset:496
	ds_read_b128 v[140:143], v26 offset:512
	ds_read_b128 v[144:147], v26 offset:528
	ds_read_b128 v[148:151], v26 offset:544
	ds_read_b128 v[152:155], v26 offset:560
	ds_read_b128 v[156:159], v26 offset:576
	ds_read_b128 v[160:163], v26 offset:592
	ds_read_b128 v[164:167], v26 offset:608
	ds_read_b128 v[168:171], v26 offset:624
	v_lshlrev_b32_e32 v0, 16, v36
	v_and_b32_e32 v1, 0xffff0000, v36
	v_lshlrev_b32_e32 v2, 16, v37
	v_and_b32_e32 v3, 0xffff0000, v37
	v_lshlrev_b32_e32 v4, 16, v38
	v_and_b32_e32 v5, 0xffff0000, v38
	v_lshlrev_b32_e32 v6, 16, v39
	v_and_b32_e32 v7, 0xffff0000, v39
	s_waitcnt lgkmcnt(10)
; __device__ __forceinline__ void cb_item(const bf16_t* WT, int ldw, int K, int n0, const float* shift, float* out, int ostride, int lane) {
;     ...
;     for (int k8 = 0; k8 < K; k8 += 8) {
;         const u32x4 q = *(const u32x4*)(wp + k8);
;         float w[8];
; #pragma unroll
;         for (int e = 0; e < 4; ++e) { w[2 * e] = __uint_as_float(q[e] << 16); w[2 * e + 1] = __uint_as_float(q[e] & 0xffff0000u); }
; #pragma unroll
;         for (int b = 0; b < 5; ++b) { const float* sp = shift + (size_t)b * 9216 + k8;
; #pragma unroll
;             for (int e = 0; e < 8; ++e) a[b] += w[e] * sp[e]; }
;     }
	v_pk_fma_f32 v[196:197], v[0:1], v[92:93], v[196:197]
	v_pk_fma_f32 v[198:199], v[0:1], v[100:101], v[198:199]
	v_pk_fma_f32 v[200:201], v[0:1], v[108:109], v[200:201]
	v_pk_fma_f32 v[202:203], v[0:1], v[116:117], v[202:203]
	v_pk_fma_f32 v[204:205], v[0:1], v[124:125], v[204:205]
	v_pk_fma_f32 v[196:197], v[2:3], v[94:95], v[196:197]
	v_pk_fma_f32 v[198:199], v[2:3], v[102:103], v[198:199]
	v_pk_fma_f32 v[200:201], v[2:3], v[110:111], v[200:201]
	v_pk_fma_f32 v[202:203], v[2:3], v[118:119], v[202:203]
	v_pk_fma_f32 v[204:205], v[2:3], v[126:127], v[204:205]
	v_pk_fma_f32 v[196:197], v[4:5], v[96:97], v[196:197]
	v_pk_fma_f32 v[198:199], v[4:5], v[104:105], v[198:199]
	v_pk_fma_f32 v[200:201], v[4:5], v[112:113], v[200:201]
	v_pk_fma_f32 v[202:203], v[4:5], v[120:121], v[202:203]
	v_pk_fma_f32 v[204:205], v[4:5], v[128:129], v[204:205]
	v_pk_fma_f32 v[196:197], v[6:7], v[98:99], v[196:197]
	v_pk_fma_f32 v[198:199], v[6:7], v[106:107], v[198:199]
	v_pk_fma_f32 v[200:201], v[6:7], v[114:115], v[200:201]
	v_pk_fma_f32 v[202:203], v[6:7], v[122:123], v[202:203]
	v_pk_fma_f32 v[204:205], v[6:7], v[130:131], v[204:205]
	ds_read_b128 v[92:95], v26 offset:640
	ds_read_b128 v[96:99], v26 offset:656
	ds_read_b128 v[100:103], v26 offset:672
	ds_read_b128 v[104:107], v26 offset:688
	ds_read_b128 v[108:111], v26 offset:704
	ds_read_b128 v[112:115], v26 offset:720
	ds_read_b128 v[116:119], v26 offset:736
	ds_read_b128 v[120:123], v26 offset:752
	ds_read_b128 v[124:127], v26 offset:768
	ds_read_b128 v[128:131], v26 offset:784
	v_lshlrev_b32_e32 v0, 16, v40
	v_and_b32_e32 v1, 0xffff0000, v40
	v_lshlrev_b32_e32 v2, 16, v41
	v_and_b32_e32 v3, 0xffff0000, v41
	v_lshlrev_b32_e32 v4, 16, v42
	v_and_b32_e32 v5, 0xffff0000, v42
	v_lshlrev_b32_e32 v6, 16, v43
	v_and_b32_e32 v7, 0xffff0000, v43
	s_waitcnt lgkmcnt(10)
	v_pk_fma_f32 v[196:197], v[0:1], v[132:133], v[196:197]
	v_pk_fma_f32 v[198:199], v[0:1], v[140:141], v[198:199]
	v_pk_fma_f32 v[200:201], v[0:1], v[148:149], v[200:201]
	v_pk_fma_f32 v[202:203], v[0:1], v[156:157], v[202:203]
	v_pk_fma_f32 v[204:205], v[0:1], v[164:165], v[204:205]
	v_pk_fma_f32 v[196:197], v[2:3], v[134:135], v[196:197]
	v_pk_fma_f32 v[198:199], v[2:3], v[142:143], v[198:199]
	v_pk_fma_f32 v[200:201], v[2:3], v[150:151], v[200:201]
	v_pk_fma_f32 v[202:203], v[2:3], v[158:159], v[202:203]
	v_pk_fma_f32 v[204:205], v[2:3], v[166:167], v[204:205]
	v_pk_fma_f32 v[196:197], v[4:5], v[136:137], v[196:197]
	v_pk_fma_f32 v[198:199], v[4:5], v[144:145], v[198:199]
	v_pk_fma_f32 v[200:201], v[4:5], v[152:153], v[200:201]
	v_pk_fma_f32 v[202:203], v[4:5], v[160:161], v[202:203]
	v_pk_fma_f32 v[204:205], v[4:5], v[168:169], v[204:205]
	v_pk_fma_f32 v[196:197], v[6:7], v[138:139], v[196:197]
	v_pk_fma_f32 v[198:199], v[6:7], v[146:147], v[198:199]
	v_pk_fma_f32 v[200:201], v[6:7], v[154:155], v[200:201]
	v_pk_fma_f32 v[202:203], v[6:7], v[162:163], v[202:203]
	v_pk_fma_f32 v[204:205], v[6:7], v[170:171], v[204:205]
	ds_read_b128 v[132:135], v26 offset:800
	ds_read_b128 v[136:139], v26 offset:816
	ds_read_b128 v[140:143], v26 offset:832
	ds_read_b128 v[144:147], v26 offset:848
	ds_read_b128 v[148:151], v26 offset:864
	ds_read_b128 v[152:155], v26 offset:880
	ds_read_b128 v[156:159], v26 offset:896
	ds_read_b128 v[160:163], v26 offset:912
	ds_read_b128 v[164:167], v26 offset:928
	ds_read_b128 v[168:171], v26 offset:944
	v_lshlrev_b32_e32 v0, 16, v44
	v_and_b32_e32 v1, 0xffff0000, v44
	v_lshlrev_b32_e32 v2, 16, v45
	v_and_b32_e32 v3, 0xffff0000, v45
	v_lshlrev_b32_e32 v4, 16, v46
	v_and_b32_e32 v5, 0xffff0000, v46
	v_lshlrev_b32_e32 v6, 16, v47
	v_and_b32_e32 v7, 0xffff0000, v47
	s_waitcnt lgkmcnt(10)
	v_pk_fma_f32 v[196:197], v[0:1], v[92:93], v[196:197]
	v_pk_fma_f32 v[198:199], v[0:1], v[100:101], v[198:199]
	v_pk_fma_f32 v[200:201], v[0:1], v[108:109], v[200:201]
	v_pk_fma_f32 v[202:203], v[0:1], v[116:117], v[202:203]
	v_pk_fma_f32 v[204:205], v[0:1], v[124:125], v[204:205]
	v_pk_fma_f32 v[196:197], v[2:3], v[94:95], v[196:197]
	v_pk_fma_f32 v[198:199], v[2:3], v[102:103], v[198:199]
	v_pk_fma_f32 v[200:201], v[2:3], v[110:111], v[200:201]
	v_pk_fma_f32 v[202:203], v[2:3], v[118:119], v[202:203]
	v_pk_fma_f32 v[204:205], v[2:3], v[126:127], v[204:205]
	v_pk_fma_f32 v[196:197], v[4:5], v[96:97], v[196:197]
	v_pk_fma_f32 v[198:199], v[4:5], v[104:105], v[198:199]
	v_pk_fma_f32 v[200:201], v[4:5], v[112:113], v[200:201]
	v_pk_fma_f32 v[202:203], v[4:5], v[120:121], v[202:203]
	v_pk_fma_f32 v[204:205], v[4:5], v[128:129], v[204:205]
	v_pk_fma_f32 v[196:197], v[6:7], v[98:99], v[196:197]
	v_pk_fma_f32 v[198:199], v[6:7], v[106:107], v[198:199]
	v_pk_fma_f32 v[200:201], v[6:7], v[114:115], v[200:201]
	v_pk_fma_f32 v[202:203], v[6:7], v[122:123], v[202:203]
	v_pk_fma_f32 v[204:205], v[6:7], v[130:131], v[204:205]
	ds_read_b128 v[92:95], v26 offset:960
	ds_read_b128 v[96:99], v26 offset:976
	ds_read_b128 v[100:103], v26 offset:992
	ds_read_b128 v[104:107], v26 offset:1008
	ds_read_b128 v[108:111], v26 offset:1024
	ds_read_b128 v[112:115], v26 offset:1040
	ds_read_b128 v[116:119], v26 offset:1056
	ds_read_b128 v[120:123], v26 offset:1072
	ds_read_b128 v[124:127], v26 offset:1088
	ds_read_b128 v[128:131], v26 offset:1104
	v_lshlrev_b32_e32 v0, 16, v48
	v_and_b32_e32 v1, 0xffff0000, v48
	v_lshlrev_b32_e32 v2, 16, v49
	v_and_b32_e32 v3, 0xffff0000, v49
	v_lshlrev_b32_e32 v4, 16, v50
	v_and_b32_e32 v5, 0xffff0000, v50
	v_lshlrev_b32_e32 v6, 16, v51
	v_and_b32_e32 v7, 0xffff0000, v51
	s_waitcnt lgkmcnt(10)
; __device__ __forceinline__ void cb_item(const bf16_t* WT, int ldw, int K, int n0, const float* shift, float* out, int ostride, int lane) {
;     ...
;     for (int k8 = 0; k8 < K; k8 += 8) {
;         const u32x4 q = *(const u32x4*)(wp + k8);
;         float w[8];
; #pragma unroll
;         for (int e = 0; e < 4; ++e) { w[2 * e] = __uint_as_float(q[e] << 16); w[2 * e + 1] = __uint_as_float(q[e] & 0xffff0000u); }
; #pragma unroll
;         for (int b = 0; b < 5; ++b) { const float* sp = shift + (size_t)b * 9216 + k8;
; #pragma unroll
;             for (int e = 0; e < 8; ++e) a[b] += w[e] * sp[e]; }
;     }
	v_pk_fma_f32 v[196:197], v[0:1], v[132:133], v[196:197]
	v_pk_fma_f32 v[198:199], v[0:1], v[140:141], v[198:199]
	v_pk_fma_f32 v[200:201], v[0:1], v[148:149], v[200:201]
	v_pk_fma_f32 v[202:203], v[0:1], v[156:157], v[202:203]
	v_pk_fma_f32 v[204:205], v[0:1], v[164:165], v[204:205]
	v_pk_fma_f32 v[196:197], v[2:3], v[134:135], v[196:197]
	v_pk_fma_f32 v[198:199], v[2:3], v[142:143], v[198:199]
	v_pk_fma_f32 v[200:201], v[2:3], v[150:151], v[200:201]
	v_pk_fma_f32 v[202:203], v[2:3], v[158:159], v[202:203]
	v_pk_fma_f32 v[204:205], v[2:3], v[166:167], v[204:205]
	v_pk_fma_f32 v[196:197], v[4:5], v[136:137], v[196:197]
	v_pk_fma_f32 v[198:199], v[4:5], v[144:145], v[198:199]
	v_pk_fma_f32 v[200:201], v[4:5], v[152:153], v[200:201]
	v_pk_fma_f32 v[202:203], v[4:5], v[160:161], v[202:203]
	v_pk_fma_f32 v[204:205], v[4:5], v[168:169], v[204:205]
	v_pk_fma_f32 v[196:197], v[6:7], v[138:139], v[196:197]
	v_pk_fma_f32 v[198:199], v[6:7], v[146:147], v[198:199]
	v_pk_fma_f32 v[200:201], v[6:7], v[154:155], v[200:201]
	v_pk_fma_f32 v[202:203], v[6:7], v[162:163], v[202:203]
	v_pk_fma_f32 v[204:205], v[6:7], v[170:171], v[204:205]
	ds_read_b128 v[132:135], v26 offset:1120
	ds_read_b128 v[136:139], v26 offset:1136
	ds_read_b128 v[140:143], v26 offset:1152
	ds_read_b128 v[144:147], v26 offset:1168
	ds_read_b128 v[148:151], v26 offset:1184
	ds_read_b128 v[152:155], v26 offset:1200
	ds_read_b128 v[156:159], v26 offset:1216
	ds_read_b128 v[160:163], v26 offset:1232
	ds_read_b128 v[164:167], v26 offset:1248
	ds_read_b128 v[168:171], v26 offset:1264
	v_lshlrev_b32_e32 v0, 16, v52
	v_and_b32_e32 v1, 0xffff0000, v52
	v_lshlrev_b32_e32 v2, 16, v53
	v_and_b32_e32 v3, 0xffff0000, v53
	v_lshlrev_b32_e32 v4, 16, v54
	v_and_b32_e32 v5, 0xffff0000, v54
	v_lshlrev_b32_e32 v6, 16, v55
	v_and_b32_e32 v7, 0xffff0000, v55
	s_waitcnt lgkmcnt(10)
	v_pk_fma_f32 v[196:197], v[0:1], v[92:93], v[196:197]
	v_pk_fma_f32 v[198:199], v[0:1], v[100:101], v[198:199]
	v_pk_fma_f32 v[200:201], v[0:1], v[108:109], v[200:201]
	v_pk_fma_f32 v[202:203], v[0:1], v[116:117], v[202:203]
	v_pk_fma_f32 v[204:205], v[0:1], v[124:125], v[204:205]
	v_pk_fma_f32 v[196:197], v[2:3], v[94:95], v[196:197]
	v_pk_fma_f32 v[198:199], v[2:3], v[102:103], v[198:199]
	v_pk_fma_f32 v[200:201], v[2:3], v[110:111], v[200:201]
	v_pk_fma_f32 v[202:203], v[2:3], v[118:119], v[202:203]
	v_pk_fma_f32 v[204:205], v[2:3], v[126:127], v[204:205]
	v_pk_fma_f32 v[196:197], v[4:5], v[96:97], v[196:197]
	v_pk_fma_f32 v[198:199], v[4:5], v[104:105], v[198:199]
	v_pk_fma_f32 v[200:201], v[4:5], v[112:113], v[200:201]
	v_pk_fma_f32 v[202:203], v[4:5], v[120:121], v[202:203]
	v_pk_fma_f32 v[204:205], v[4:5], v[128:129], v[204:205]
	v_pk_fma_f32 v[196:197], v[6:7], v[98:99], v[196:197]
	v_pk_fma_f32 v[198:199], v[6:7], v[106:107], v[198:199]
	v_pk_fma_f32 v[200:201], v[6:7], v[114:115], v[200:201]
	v_pk_fma_f32 v[202:203], v[6:7], v[122:123], v[202:203]
	v_pk_fma_f32 v[204:205], v[6:7], v[130:131], v[204:205]
	ds_read_b128 v[92:95], v26 offset:1280
	ds_read_b128 v[96:99], v26 offset:1296
	ds_read_b128 v[100:103], v26 offset:1312
	ds_read_b128 v[104:107], v26 offset:1328
	ds_read_b128 v[108:111], v26 offset:1344
	ds_read_b128 v[112:115], v26 offset:1360
	ds_read_b128 v[116:119], v26 offset:1376
	ds_read_b128 v[120:123], v26 offset:1392
	ds_read_b128 v[124:127], v26 offset:1408
	ds_read_b128 v[128:131], v26 offset:1424
	v_lshlrev_b32_e32 v0, 16, v56
	v_and_b32_e32 v1, 0xffff0000, v56
	v_lshlrev_b32_e32 v2, 16, v57
	v_and_b32_e32 v3, 0xffff0000, v57
	v_lshlrev_b32_e32 v4, 16, v58
	v_and_b32_e32 v5, 0xffff0000, v58
	v_lshlrev_b32_e32 v6, 16, v59
	v_and_b32_e32 v7, 0xffff0000, v59
	s_waitcnt lgkmcnt(10)
	v_pk_fma_f32 v[196:197], v[0:1], v[132:133], v[196:197]
	v_pk_fma_f32 v[198:199], v[0:1], v[140:141], v[198:199]
	v_pk_fma_f32 v[200:201], v[0:1], v[148:149], v[200:201]
	v_pk_fma_f32 v[202:203], v[0:1], v[156:157], v[202:203]
	v_pk_fma_f32 v[204:205], v[0:1], v[164:165], v[204:205]
	v_pk_fma_f32 v[196:197], v[2:3], v[134:135], v[196:197]
	v_pk_fma_f32 v[198:199], v[2:3], v[142:143], v[198:199]
	v_pk_fma_f32 v[200:201], v[2:3], v[150:151], v[200:201]
	v_pk_fma_f32 v[202:203], v[2:3], v[158:159], v[202:203]
	v_pk_fma_f32 v[204:205], v[2:3], v[166:167], v[204:205]
	v_pk_fma_f32 v[196:197], v[4:5], v[136:137], v[196:197]
	v_pk_fma_f32 v[198:199], v[4:5], v[144:145], v[198:199]
	v_pk_fma_f32 v[200:201], v[4:5], v[152:153], v[200:201]
	v_pk_fma_f32 v[202:203], v[4:5], v[160:161], v[202:203]
	v_pk_fma_f32 v[204:205], v[4:5], v[168:169], v[204:205]
	v_pk_fma_f32 v[196:197], v[6:7], v[138:139], v[196:197]
	v_pk_fma_f32 v[198:199], v[6:7], v[146:147], v[198:199]
	v_pk_fma_f32 v[200:201], v[6:7], v[154:155], v[200:201]
	v_pk_fma_f32 v[202:203], v[6:7], v[162:163], v[202:203]
	v_pk_fma_f32 v[204:205], v[6:7], v[170:171], v[204:205]
	ds_read_b128 v[132:135], v26 offset:1440
	ds_read_b128 v[136:139], v26 offset:1456
	ds_read_b128 v[140:143], v26 offset:1472
	ds_read_b128 v[144:147], v26 offset:1488
	ds_read_b128 v[148:151], v26 offset:1504
	ds_read_b128 v[152:155], v26 offset:1520
	ds_read_b128 v[156:159], v26 offset:1536
	ds_read_b128 v[160:163], v26 offset:1552
	ds_read_b128 v[164:167], v26 offset:1568
	ds_read_b128 v[168:171], v26 offset:1584
	v_lshlrev_b32_e32 v0, 16, v60
	v_and_b32_e32 v1, 0xffff0000, v60
	v_lshlrev_b32_e32 v2, 16, v61
	v_and_b32_e32 v3, 0xffff0000, v61
	v_lshlrev_b32_e32 v4, 16, v62
	v_and_b32_e32 v5, 0xffff0000, v62
	v_lshlrev_b32_e32 v6, 16, v63
	v_and_b32_e32 v7, 0xffff0000, v63
	s_waitcnt lgkmcnt(10)
; __device__ __forceinline__ void cb_item(const bf16_t* WT, int ldw, int K, int n0, const float* shift, float* out, int ostride, int lane) {
;     ...
;     for (int k8 = 0; k8 < K; k8 += 8) {
;         const u32x4 q = *(const u32x4*)(wp + k8);
;         float w[8];
; #pragma unroll
;         for (int e = 0; e < 4; ++e) { w[2 * e] = __uint_as_float(q[e] << 16); w[2 * e + 1] = __uint_as_float(q[e] & 0xffff0000u); }
; #pragma unroll
;         for (int b = 0; b < 5; ++b) { const float* sp = shift + (size_t)b * 9216 + k8;
; #pragma unroll
;             for (int e = 0; e < 8; ++e) a[b] += w[e] * sp[e]; }
;     }
	v_pk_fma_f32 v[196:197], v[0:1], v[92:93], v[196:197]
	v_pk_fma_f32 v[198:199], v[0:1], v[100:101], v[198:199]
	v_pk_fma_f32 v[200:201], v[0:1], v[108:109], v[200:201]
	v_pk_fma_f32 v[202:203], v[0:1], v[116:117], v[202:203]
	v_pk_fma_f32 v[204:205], v[0:1], v[124:125], v[204:205]
	v_pk_fma_f32 v[196:197], v[2:3], v[94:95], v[196:197]
	v_pk_fma_f32 v[198:199], v[2:3], v[102:103], v[198:199]
	v_pk_fma_f32 v[200:201], v[2:3], v[110:111], v[200:201]
	v_pk_fma_f32 v[202:203], v[2:3], v[118:119], v[202:203]
	v_pk_fma_f32 v[204:205], v[2:3], v[126:127], v[204:205]
	v_pk_fma_f32 v[196:197], v[4:5], v[96:97], v[196:197]
	v_pk_fma_f32 v[198:199], v[4:5], v[104:105], v[198:199]
	v_pk_fma_f32 v[200:201], v[4:5], v[112:113], v[200:201]
	v_pk_fma_f32 v[202:203], v[4:5], v[120:121], v[202:203]
	v_pk_fma_f32 v[204:205], v[4:5], v[128:129], v[204:205]
	v_pk_fma_f32 v[196:197], v[6:7], v[98:99], v[196:197]
	v_pk_fma_f32 v[198:199], v[6:7], v[106:107], v[198:199]
	v_pk_fma_f32 v[200:201], v[6:7], v[114:115], v[200:201]
	v_pk_fma_f32 v[202:203], v[6:7], v[122:123], v[202:203]
	v_pk_fma_f32 v[204:205], v[6:7], v[130:131], v[204:205]
	ds_read_b128 v[92:95], v26 offset:1600
	ds_read_b128 v[96:99], v26 offset:1616
	ds_read_b128 v[100:103], v26 offset:1632
	ds_read_b128 v[104:107], v26 offset:1648
	ds_read_b128 v[108:111], v26 offset:1664
	ds_read_b128 v[112:115], v26 offset:1680
	ds_read_b128 v[116:119], v26 offset:1696
	ds_read_b128 v[120:123], v26 offset:1712
	ds_read_b128 v[124:127], v26 offset:1728
	ds_read_b128 v[128:131], v26 offset:1744
	v_lshlrev_b32_e32 v0, 16, v64
	v_and_b32_e32 v1, 0xffff0000, v64
	v_lshlrev_b32_e32 v2, 16, v65
	v_and_b32_e32 v3, 0xffff0000, v65
	v_lshlrev_b32_e32 v4, 16, v66
	v_and_b32_e32 v5, 0xffff0000, v66
	v_lshlrev_b32_e32 v6, 16, v67
	v_and_b32_e32 v7, 0xffff0000, v67
	s_waitcnt lgkmcnt(10)
	v_pk_fma_f32 v[196:197], v[0:1], v[132:133], v[196:197]
	v_pk_fma_f32 v[198:199], v[0:1], v[140:141], v[198:199]
	v_pk_fma_f32 v[200:201], v[0:1], v[148:149], v[200:201]
	v_pk_fma_f32 v[202:203], v[0:1], v[156:157], v[202:203]
	v_pk_fma_f32 v[204:205], v[0:1], v[164:165], v[204:205]
	v_pk_fma_f32 v[196:197], v[2:3], v[134:135], v[196:197]
	v_pk_fma_f32 v[198:199], v[2:3], v[142:143], v[198:199]
	v_pk_fma_f32 v[200:201], v[2:3], v[150:151], v[200:201]
	v_pk_fma_f32 v[202:203], v[2:3], v[158:159], v[202:203]
	v_pk_fma_f32 v[204:205], v[2:3], v[166:167], v[204:205]
	v_pk_fma_f32 v[196:197], v[4:5], v[136:137], v[196:197]
	v_pk_fma_f32 v[198:199], v[4:5], v[144:145], v[198:199]
	v_pk_fma_f32 v[200:201], v[4:5], v[152:153], v[200:201]
	v_pk_fma_f32 v[202:203], v[4:5], v[160:161], v[202:203]
	v_pk_fma_f32 v[204:205], v[4:5], v[168:169], v[204:205]
	v_pk_fma_f32 v[196:197], v[6:7], v[138:139], v[196:197]
	v_pk_fma_f32 v[198:199], v[6:7], v[146:147], v[198:199]
	v_pk_fma_f32 v[200:201], v[6:7], v[154:155], v[200:201]
	v_pk_fma_f32 v[202:203], v[6:7], v[162:163], v[202:203]
	v_pk_fma_f32 v[204:205], v[6:7], v[170:171], v[204:205]
	ds_read_b128 v[132:135], v26 offset:1760
	ds_read_b128 v[136:139], v26 offset:1776
	ds_read_b128 v[140:143], v26 offset:1792
	ds_read_b128 v[144:147], v26 offset:1808
	ds_read_b128 v[148:151], v26 offset:1824
	ds_read_b128 v[152:155], v26 offset:1840
	ds_read_b128 v[156:159], v26 offset:1856
	ds_read_b128 v[160:163], v26 offset:1872
	ds_read_b128 v[164:167], v26 offset:1888
	ds_read_b128 v[168:171], v26 offset:1904
	v_lshlrev_b32_e32 v0, 16, v68
	v_and_b32_e32 v1, 0xffff0000, v68
	v_lshlrev_b32_e32 v2, 16, v69
	v_and_b32_e32 v3, 0xffff0000, v69
	v_lshlrev_b32_e32 v4, 16, v70
	v_and_b32_e32 v5, 0xffff0000, v70
	v_lshlrev_b32_e32 v6, 16, v71
	v_and_b32_e32 v7, 0xffff0000, v71
	s_waitcnt lgkmcnt(10)
	v_pk_fma_f32 v[196:197], v[0:1], v[92:93], v[196:197]
	v_pk_fma_f32 v[198:199], v[0:1], v[100:101], v[198:199]
	v_pk_fma_f32 v[200:201], v[0:1], v[108:109], v[200:201]
	v_pk_fma_f32 v[202:203], v[0:1], v[116:117], v[202:203]
	v_pk_fma_f32 v[204:205], v[0:1], v[124:125], v[204:205]
	v_pk_fma_f32 v[196:197], v[2:3], v[94:95], v[196:197]
	v_pk_fma_f32 v[198:199], v[2:3], v[102:103], v[198:199]
	v_pk_fma_f32 v[200:201], v[2:3], v[110:111], v[200:201]
	v_pk_fma_f32 v[202:203], v[2:3], v[118:119], v[202:203]
	v_pk_fma_f32 v[204:205], v[2:3], v[126:127], v[204:205]
	v_pk_fma_f32 v[196:197], v[4:5], v[96:97], v[196:197]
	v_pk_fma_f32 v[198:199], v[4:5], v[104:105], v[198:199]
	v_pk_fma_f32 v[200:201], v[4:5], v[112:113], v[200:201]
	v_pk_fma_f32 v[202:203], v[4:5], v[120:121], v[202:203]
	v_pk_fma_f32 v[204:205], v[4:5], v[128:129], v[204:205]
	v_pk_fma_f32 v[196:197], v[6:7], v[98:99], v[196:197]
	v_pk_fma_f32 v[198:199], v[6:7], v[106:107], v[198:199]
	v_pk_fma_f32 v[200:201], v[6:7], v[114:115], v[200:201]
	v_pk_fma_f32 v[202:203], v[6:7], v[122:123], v[202:203]
	v_pk_fma_f32 v[204:205], v[6:7], v[130:131], v[204:205]
	ds_read_b128 v[92:95], v26 offset:1920
	ds_read_b128 v[96:99], v26 offset:1936
	ds_read_b128 v[100:103], v26 offset:1952
	ds_read_b128 v[104:107], v26 offset:1968
	ds_read_b128 v[108:111], v26 offset:1984
	ds_read_b128 v[112:115], v26 offset:2000
	ds_read_b128 v[116:119], v26 offset:2016
	ds_read_b128 v[120:123], v26 offset:2032
	ds_read_b128 v[124:127], v26 offset:2048
	ds_read_b128 v[128:131], v26 offset:2064
	v_lshlrev_b32_e32 v0, 16, v72
	v_and_b32_e32 v1, 0xffff0000, v72
	v_lshlrev_b32_e32 v2, 16, v73
	v_and_b32_e32 v3, 0xffff0000, v73
	v_lshlrev_b32_e32 v4, 16, v74
	v_and_b32_e32 v5, 0xffff0000, v74
	v_lshlrev_b32_e32 v6, 16, v75
	v_and_b32_e32 v7, 0xffff0000, v75
	s_waitcnt lgkmcnt(10)
; __device__ __forceinline__ void cb_item(const bf16_t* WT, int ldw, int K, int n0, const float* shift, float* out, int ostride, int lane) {
;     ...
;     for (int k8 = 0; k8 < K; k8 += 8) {
;         const u32x4 q = *(const u32x4*)(wp + k8);
;         float w[8];
; #pragma unroll
;         for (int e = 0; e < 4; ++e) { w[2 * e] = __uint_as_float(q[e] << 16); w[2 * e + 1] = __uint_as_float(q[e] & 0xffff0000u); }
; #pragma unroll
;         for (int b = 0; b < 5; ++b) { const float* sp = shift + (size_t)b * 9216 + k8;
; #pragma unroll
;             for (int e = 0; e < 8; ++e) a[b] += w[e] * sp[e]; }
;     }
	v_pk_fma_f32 v[196:197], v[0:1], v[132:133], v[196:197]
	v_pk_fma_f32 v[198:199], v[0:1], v[140:141], v[198:199]
	v_pk_fma_f32 v[200:201], v[0:1], v[148:149], v[200:201]
	v_pk_fma_f32 v[202:203], v[0:1], v[156:157], v[202:203]
	v_pk_fma_f32 v[204:205], v[0:1], v[164:165], v[204:205]
	v_pk_fma_f32 v[196:197], v[2:3], v[134:135], v[196:197]
	v_pk_fma_f32 v[198:199], v[2:3], v[142:143], v[198:199]
	v_pk_fma_f32 v[200:201], v[2:3], v[150:151], v[200:201]
	v_pk_fma_f32 v[202:203], v[2:3], v[158:159], v[202:203]
	v_pk_fma_f32 v[204:205], v[2:3], v[166:167], v[204:205]
	v_pk_fma_f32 v[196:197], v[4:5], v[136:137], v[196:197]
	v_pk_fma_f32 v[198:199], v[4:5], v[144:145], v[198:199]
	v_pk_fma_f32 v[200:201], v[4:5], v[152:153], v[200:201]
	v_pk_fma_f32 v[202:203], v[4:5], v[160:161], v[202:203]
	v_pk_fma_f32 v[204:205], v[4:5], v[168:169], v[204:205]
	v_pk_fma_f32 v[196:197], v[6:7], v[138:139], v[196:197]
	v_pk_fma_f32 v[198:199], v[6:7], v[146:147], v[198:199]
	v_pk_fma_f32 v[200:201], v[6:7], v[154:155], v[200:201]
	v_pk_fma_f32 v[202:203], v[6:7], v[162:163], v[202:203]
	v_pk_fma_f32 v[204:205], v[6:7], v[170:171], v[204:205]
	ds_read_b128 v[132:135], v26 offset:2080
	ds_read_b128 v[136:139], v26 offset:2096
	ds_read_b128 v[140:143], v26 offset:2112
	ds_read_b128 v[144:147], v26 offset:2128
	ds_read_b128 v[148:151], v26 offset:2144
	ds_read_b128 v[152:155], v26 offset:2160
	ds_read_b128 v[156:159], v26 offset:2176
	ds_read_b128 v[160:163], v26 offset:2192
	ds_read_b128 v[164:167], v26 offset:2208
	ds_read_b128 v[168:171], v26 offset:2224
	v_lshlrev_b32_e32 v0, 16, v76
	v_and_b32_e32 v1, 0xffff0000, v76
	v_lshlrev_b32_e32 v2, 16, v77
	v_and_b32_e32 v3, 0xffff0000, v77
	v_lshlrev_b32_e32 v4, 16, v78
	v_and_b32_e32 v5, 0xffff0000, v78
	v_lshlrev_b32_e32 v6, 16, v79
	v_and_b32_e32 v7, 0xffff0000, v79
	s_waitcnt lgkmcnt(10)
	v_pk_fma_f32 v[196:197], v[0:1], v[92:93], v[196:197]
	v_pk_fma_f32 v[198:199], v[0:1], v[100:101], v[198:199]
	v_pk_fma_f32 v[200:201], v[0:1], v[108:109], v[200:201]
	v_pk_fma_f32 v[202:203], v[0:1], v[116:117], v[202:203]
	v_pk_fma_f32 v[204:205], v[0:1], v[124:125], v[204:205]
	v_pk_fma_f32 v[196:197], v[2:3], v[94:95], v[196:197]
	v_pk_fma_f32 v[198:199], v[2:3], v[102:103], v[198:199]
	v_pk_fma_f32 v[200:201], v[2:3], v[110:111], v[200:201]
	v_pk_fma_f32 v[202:203], v[2:3], v[118:119], v[202:203]
	v_pk_fma_f32 v[204:205], v[2:3], v[126:127], v[204:205]
	v_pk_fma_f32 v[196:197], v[4:5], v[96:97], v[196:197]
	v_pk_fma_f32 v[198:199], v[4:5], v[104:105], v[198:199]
	v_pk_fma_f32 v[200:201], v[4:5], v[112:113], v[200:201]
	v_pk_fma_f32 v[202:203], v[4:5], v[120:121], v[202:203]
	v_pk_fma_f32 v[204:205], v[4:5], v[128:129], v[204:205]
	v_pk_fma_f32 v[196:197], v[6:7], v[98:99], v[196:197]
	v_pk_fma_f32 v[198:199], v[6:7], v[106:107], v[198:199]
	v_pk_fma_f32 v[200:201], v[6:7], v[114:115], v[200:201]
	v_pk_fma_f32 v[202:203], v[6:7], v[122:123], v[202:203]
	v_pk_fma_f32 v[204:205], v[6:7], v[130:131], v[204:205]
	ds_read_b128 v[92:95], v26 offset:2240
	ds_read_b128 v[96:99], v26 offset:2256
	ds_read_b128 v[100:103], v26 offset:2272
	ds_read_b128 v[104:107], v26 offset:2288
	ds_read_b128 v[108:111], v26 offset:2304
	ds_read_b128 v[112:115], v26 offset:2320
	ds_read_b128 v[116:119], v26 offset:2336
	ds_read_b128 v[120:123], v26 offset:2352
	ds_read_b128 v[124:127], v26 offset:2368
	ds_read_b128 v[128:131], v26 offset:2384
	v_lshlrev_b32_e32 v0, 16, v80
	v_and_b32_e32 v1, 0xffff0000, v80
	v_lshlrev_b32_e32 v2, 16, v81
	v_and_b32_e32 v3, 0xffff0000, v81
	v_lshlrev_b32_e32 v4, 16, v82
	v_and_b32_e32 v5, 0xffff0000, v82
	v_lshlrev_b32_e32 v6, 16, v83
	v_and_b32_e32 v7, 0xffff0000, v83
	s_waitcnt lgkmcnt(10)
	v_pk_fma_f32 v[196:197], v[0:1], v[132:133], v[196:197]
	v_pk_fma_f32 v[198:199], v[0:1], v[140:141], v[198:199]
	v_pk_fma_f32 v[200:201], v[0:1], v[148:149], v[200:201]
	v_pk_fma_f32 v[202:203], v[0:1], v[156:157], v[202:203]
	v_pk_fma_f32 v[204:205], v[0:1], v[164:165], v[204:205]
	v_pk_fma_f32 v[196:197], v[2:3], v[134:135], v[196:197]
	v_pk_fma_f32 v[198:199], v[2:3], v[142:143], v[198:199]
	v_pk_fma_f32 v[200:201], v[2:3], v[150:151], v[200:201]
	v_pk_fma_f32 v[202:203], v[2:3], v[158:159], v[202:203]
	v_pk_fma_f32 v[204:205], v[2:3], v[166:167], v[204:205]
	v_pk_fma_f32 v[196:197], v[4:5], v[136:137], v[196:197]
	v_pk_fma_f32 v[198:199], v[4:5], v[144:145], v[198:199]
	v_pk_fma_f32 v[200:201], v[4:5], v[152:153], v[200:201]
	v_pk_fma_f32 v[202:203], v[4:5], v[160:161], v[202:203]
	v_pk_fma_f32 v[204:205], v[4:5], v[168:169], v[204:205]
	v_pk_fma_f32 v[196:197], v[6:7], v[138:139], v[196:197]
	v_pk_fma_f32 v[198:199], v[6:7], v[146:147], v[198:199]
	v_pk_fma_f32 v[200:201], v[6:7], v[154:155], v[200:201]
	v_pk_fma_f32 v[202:203], v[6:7], v[162:163], v[202:203]
	v_pk_fma_f32 v[204:205], v[6:7], v[170:171], v[204:205]
	ds_read_b128 v[132:135], v26 offset:2400
	ds_read_b128 v[136:139], v26 offset:2416
	ds_read_b128 v[140:143], v26 offset:2432
	ds_read_b128 v[144:147], v26 offset:2448
	ds_read_b128 v[148:151], v26 offset:2464
	ds_read_b128 v[152:155], v26 offset:2480
	ds_read_b128 v[156:159], v26 offset:2496
	ds_read_b128 v[160:163], v26 offset:2512
	ds_read_b128 v[164:167], v26 offset:2528
	ds_read_b128 v[168:171], v26 offset:2544
	v_lshlrev_b32_e32 v0, 16, v84
	v_and_b32_e32 v1, 0xffff0000, v84
	v_lshlrev_b32_e32 v2, 16, v85
	v_and_b32_e32 v3, 0xffff0000, v85
	v_lshlrev_b32_e32 v4, 16, v86
	v_and_b32_e32 v5, 0xffff0000, v86
	v_lshlrev_b32_e32 v6, 16, v87
	v_and_b32_e32 v7, 0xffff0000, v87
	s_waitcnt lgkmcnt(10)
; __device__ __forceinline__ void cb_item(const bf16_t* WT, int ldw, int K, int n0, const float* shift, float* out, int ostride, int lane) {
;     ...
;     for (int k8 = 0; k8 < K; k8 += 8) {
;         const u32x4 q = *(const u32x4*)(wp + k8);
;         float w[8];
; #pragma unroll
;         for (int e = 0; e < 4; ++e) { w[2 * e] = __uint_as_float(q[e] << 16); w[2 * e + 1] = __uint_as_float(q[e] & 0xffff0000u); }
; #pragma unroll
;         for (int b = 0; b < 5; ++b) { const float* sp = shift + (size_t)b * 9216 + k8;
; #pragma unroll
;             for (int e = 0; e < 8; ++e) a[b] += w[e] * sp[e]; }
;     }
; #pragma unroll
;     for (int b = 0; b < 5; ++b) out[(size_t)b * ostride + n0 + lane] = a[b];
	v_pk_fma_f32 v[196:197], v[0:1], v[92:93], v[196:197]
	v_pk_fma_f32 v[198:199], v[0:1], v[100:101], v[198:199]
	v_pk_fma_f32 v[200:201], v[0:1], v[108:109], v[200:201]
	v_pk_fma_f32 v[202:203], v[0:1], v[116:117], v[202:203]
	v_pk_fma_f32 v[204:205], v[0:1], v[124:125], v[204:205]
	v_pk_fma_f32 v[196:197], v[2:3], v[94:95], v[196:197]
	v_pk_fma_f32 v[198:199], v[2:3], v[102:103], v[198:199]
	v_pk_fma_f32 v[200:201], v[2:3], v[110:111], v[200:201]
	v_pk_fma_f32 v[202:203], v[2:3], v[118:119], v[202:203]
	v_pk_fma_f32 v[204:205], v[2:3], v[126:127], v[204:205]
	v_pk_fma_f32 v[196:197], v[4:5], v[96:97], v[196:197]
	v_pk_fma_f32 v[198:199], v[4:5], v[104:105], v[198:199]
	v_pk_fma_f32 v[200:201], v[4:5], v[112:113], v[200:201]
	v_pk_fma_f32 v[202:203], v[4:5], v[120:121], v[202:203]
	v_pk_fma_f32 v[204:205], v[4:5], v[128:129], v[204:205]
	v_pk_fma_f32 v[196:197], v[6:7], v[98:99], v[196:197]
	v_pk_fma_f32 v[198:199], v[6:7], v[106:107], v[198:199]
	v_pk_fma_f32 v[200:201], v[6:7], v[114:115], v[200:201]
	v_pk_fma_f32 v[202:203], v[6:7], v[122:123], v[202:203]
	v_pk_fma_f32 v[204:205], v[6:7], v[130:131], v[204:205]
	v_lshlrev_b32_e32 v0, 16, v88
	v_and_b32_e32 v1, 0xffff0000, v88
	v_lshlrev_b32_e32 v2, 16, v89
	v_and_b32_e32 v3, 0xffff0000, v89
	v_lshlrev_b32_e32 v4, 16, v90
	v_and_b32_e32 v5, 0xffff0000, v90
	v_lshlrev_b32_e32 v6, 16, v91
	v_and_b32_e32 v7, 0xffff0000, v91
	s_waitcnt lgkmcnt(0)
	v_pk_fma_f32 v[196:197], v[0:1], v[132:133], v[196:197]
	v_pk_fma_f32 v[198:199], v[0:1], v[140:141], v[198:199]
	v_pk_fma_f32 v[200:201], v[0:1], v[148:149], v[200:201]
	v_pk_fma_f32 v[202:203], v[0:1], v[156:157], v[202:203]
	v_pk_fma_f32 v[204:205], v[0:1], v[164:165], v[204:205]
	v_pk_fma_f32 v[196:197], v[2:3], v[134:135], v[196:197]
	v_pk_fma_f32 v[198:199], v[2:3], v[142:143], v[198:199]
	v_pk_fma_f32 v[200:201], v[2:3], v[150:151], v[200:201]
	v_pk_fma_f32 v[202:203], v[2:3], v[158:159], v[202:203]
	v_pk_fma_f32 v[204:205], v[2:3], v[166:167], v[204:205]
	v_pk_fma_f32 v[196:197], v[4:5], v[136:137], v[196:197]
	v_pk_fma_f32 v[198:199], v[4:5], v[144:145], v[198:199]
	v_pk_fma_f32 v[200:201], v[4:5], v[152:153], v[200:201]
	v_pk_fma_f32 v[202:203], v[4:5], v[160:161], v[202:203]
	v_pk_fma_f32 v[204:205], v[4:5], v[168:169], v[204:205]
	v_pk_fma_f32 v[196:197], v[6:7], v[138:139], v[196:197]
	v_pk_fma_f32 v[198:199], v[6:7], v[146:147], v[198:199]
	v_pk_fma_f32 v[200:201], v[6:7], v[154:155], v[200:201]
	v_pk_fma_f32 v[202:203], v[6:7], v[162:163], v[202:203]
	v_pk_fma_f32 v[204:205], v[6:7], v[170:171], v[204:205]
	v_add_f32_e32 v206, v196, v197
	v_add_f32_e32 v207, v198, v199
	v_add_f32_e32 v208, v200, v201
	v_add_f32_e32 v209, v202, v203
	v_add_f32_e32 v210, v204, v205
	v_add_u32_e32 v27, v26, v20
	ds_write_b32 v27, v206 offset:10240
	ds_write_b32 v27, v207 offset:10496
	ds_write_b32 v27, v208 offset:10752
	ds_write_b32 v27, v209 offset:11008
	ds_write_b32 v27, v210 offset:11264
	s_waitcnt lgkmcnt(0)
	s_barrier
	s_cmp_lg_u32 s44, 0
	s_cbranch_scc1 .Lcbx_nw0_i1
	ds_read_b32 v28, v20 offset:10240
	ds_read_b32 v29, v20 offset:26624
	ds_read_b32 v30, v20 offset:43008
	ds_read_b32 v31, v20 offset:59392
	ds_read_b32 v32, v21 offset:10240
	ds_read_b32 v33, v21 offset:26624
	ds_read_b32 v34, v21 offset:43008
	ds_read_b32 v35, v21 offset:59392
	ds_read_b32 v36, v20 offset:10496
	ds_read_b32 v37, v20 offset:26880
	ds_read_b32 v38, v20 offset:43264
	ds_read_b32 v39, v20 offset:59648
	ds_read_b32 v40, v21 offset:10496
	ds_read_b32 v41, v21 offset:26880
	ds_read_b32 v42, v21 offset:43264
	ds_read_b32 v43, v21 offset:59648
	ds_read_b32 v44, v20 offset:10752
	ds_read_b32 v45, v20 offset:27136
	ds_read_b32 v46, v20 offset:43520
	ds_read_b32 v47, v20 offset:59904
	ds_read_b32 v48, v21 offset:10752
	ds_read_b32 v49, v21 offset:27136
	ds_read_b32 v50, v21 offset:43520
	ds_read_b32 v51, v21 offset:59904
	ds_read_b32 v52, v20 offset:11008
	ds_read_b32 v53, v20 offset:27392
	ds_read_b32 v54, v20 offset:43776
	ds_read_b32 v55, v20 offset:60160
	ds_read_b32 v56, v21 offset:11008
	ds_read_b32 v57, v21 offset:27392
	ds_read_b32 v58, v21 offset:43776
	ds_read_b32 v59, v21 offset:60160
	ds_read_b32 v60, v20 offset:11264
	ds_read_b32 v61, v20 offset:27648
	ds_read_b32 v62, v20 offset:44032
	ds_read_b32 v63, v20 offset:60416
	ds_read_b32 v64, v21 offset:11264
	ds_read_b32 v65, v21 offset:27648
	ds_read_b32 v66, v21 offset:44032
	ds_read_b32 v67, v21 offset:60416
	s_mov_b64 s[0:1], s[38:39]
	s_waitcnt lgkmcnt(15)
	v_add_f32_e32 v206, v28, v29
	v_add_f32_e32 v206, v206, v30
	v_add_f32_e32 v206, v206, v31
	v_add_f32_e32 v206, v206, v32
	v_add_f32_e32 v206, v206, v33
	v_add_f32_e32 v206, v206, v34
	v_add_f32_e32 v206, v206, v35
	global_store_dword v20, v206, s[0:1]
	s_add_u32 s0, s0, s40
	s_addc_u32 s1, s1, 0
	s_waitcnt lgkmcnt(15)
	v_add_f32_e32 v207, v36, v37
	v_add_f32_e32 v207, v207, v38
	v_add_f32_e32 v207, v207, v39
	v_add_f32_e32 v207, v207, v40
	v_add_f32_e32 v207, v207, v41
	v_add_f32_e32 v207, v207, v42
	v_add_f32_e32 v207, v207, v43
	global_store_dword v20, v207, s[0:1]
	s_add_u32 s0, s0, s40
	s_addc_u32 s1, s1, 0
	s_waitcnt lgkmcnt(15)
	v_add_f32_e32 v208, v44, v45
	v_add_f32_e32 v208, v208, v46
	v_add_f32_e32 v208, v208, v47
	v_add_f32_e32 v208, v208, v48
	v_add_f32_e32 v208, v208, v49
	v_add_f32_e32 v208, v208, v50
	v_add_f32_e32 v208, v208, v51
	global_store_dword v20, v208, s[0:1]
	s_add_u32 s0, s0, s40
	s_addc_u32 s1, s1, 0
	s_waitcnt lgkmcnt(8)
	v_add_f32_e32 v209, v52, v53
	v_add_f32_e32 v209, v209, v54
	v_add_f32_e32 v209, v209, v55
	v_add_f32_e32 v209, v209, v56
	v_add_f32_e32 v209, v209, v57
	v_add_f32_e32 v209, v209, v58
	v_add_f32_e32 v209, v209, v59
	global_store_dword v20, v209, s[0:1]
	s_add_u32 s0, s0, s40
	s_addc_u32 s1, s1, 0
	s_waitcnt lgkmcnt(0)
	v_add_f32_e32 v210, v60, v61
	v_add_f32_e32 v210, v210, v62
	v_add_f32_e32 v210, v210, v63
	v_add_f32_e32 v210, v210, v64
	v_add_f32_e32 v210, v210, v65
	v_add_f32_e32 v210, v210, v66
	v_add_f32_e32 v210, v210, v67
	global_store_dword v20, v210, s[0:1]

; __device__ __forceinline__ void cb_tables(const Params& p) {
;     const int lane = threadIdx.x & 63, wave = threadIdx.x >> 6, G = gridDim.x;
;     unsigned char* ws = p.ws; const float* MOD = (const float*)(ws + WS_MOD);
;     for (int it = blockIdx.x + G * wave; it < 4 * 88 + 40 + 32; it += 8 * G) {
;         if (it < 352) { const int mi = it / 88, ch = it % 88, layer = mi >> 1, sub = mi & 1;
.Lcbx_fin:
	s_mov_b64 exec, s[100:101]
.Lcbx_done:
	v_mul_lo_u32 v0, s82, v218
	v_add_u32_e32 v193, s84, v0
	s_movk_i32 s0, 0x1a8
	v_cmp_gt_i32_e32 vcc, s0, v193
	v_lshlrev_b32_e32 v182, 2, v178
	s_and_saveexec_b64 s[12:13], vcc
	s_cbranch_execz .LBB0_165
	v_mov_b32_e32 v197, 0
	s_add_u32 s20, s80, 0x17a800
	v_mov_b32_e32 v183, v197
	s_addc_u32 s21, s81, 0
	v_lshl_add_u64 v[0:1], s[80:81], 0, v[182:183]
	s_mov_b64 s[0:1], 0x16e000
	v_lshlrev_b32_e32 v183, 6, v193
	v_lshl_add_u64 v[198:199], v[0:1], 0, s[0:1]
	s_add_u32 s22, s80, 0x100000
	v_lshlrev_b32_e32 v0, 8, v178
	v_or_b32_e32 v1, v183, v178
	s_addc_u32 s23, s81, 0
	v_add_u32_e32 v195, 0xfffffe78, v193
	v_add_u32_e32 v200, 0xffffa800, v1
	s_mov_b64 s[24:25], 0
	v_lshlrev_b32_e32 v208, 1, v0
	s_mov_b64 s[26:27], 0x80
	v_mov_b32_e32 v209, 0x27000
	v_mov_b32_e32 v210, 0x3000
	v_mov_b32_e32 v211, 0xc000
	v_mov_b32_e32 v212, 0x15000
	v_mov_b32_e32 v213, 0x1e000
	s_mov_b32 s19, 0x9000
	s_mov_b64 s[30:31], 0x12000
	s_mov_b64 s[34:35], 0x1b000
	s_mov_b64 s[36:37], 0x24000
	s_mov_b32 s33, 0x24000
	s_mov_b32 s54, 0x12000
	s_mov_b32 s55, 0x1b000
	s_mov_b64 s[38:39], 0x9040
	s_mov_b64 s[40:41], 0x12040
	s_mov_b64 s[42:43], 0x1b040
	s_mov_b64 s[44:45], 0x24040
	s_mov_b32 s56, 0x1b800
	s_movk_i32 s57, 0x1a7
	v_mov_b32_e32 v214, 0xffff9e00
	v_mov_b32_e32 v215, 0xffffa800
	s_branch .LBB0_151

; __device__ __forceinline__ void cb_tables(const Params& p) {
;     ...
;     for (int it = blockIdx.x + G * wave; it < 4 * 88 + 40 + 32; it += 8 * G) {
;         if (it < 352) { const int mi = it / 88, ch = it % 88, layer = mi >> 1, sub = mi & 1;
.LBB0_151:
	s_cmpk_lg_u32 s82, 0x100
	s_cbranch_scc1 .Lcb_noskip
	v_readfirstlane_b32 s98, v193
	s_cmpk_ge_u32 s98, 0x188
	s_cbranch_scc1 .Lcb_noskip
	s_mov_b64 s[46:47], exec
	s_branch .LBB0_150
